# SP0: every s_setprio removed from the 8 clean GEMM K-loops (equal priority for MFMA and load segments); on top of BE1
# speedup vs baseline: 1.0037x; 1.0010x over previous
.LBB0_287:
	ds_read_b128 v[136:139], v2
	ds_read_b128 v[140:143], v2 offset:1024
	ds_read_b128 v[144:147], v2 offset:2048
	ds_read_b128 v[148:151], v2 offset:3072
	ds_read_b128 v[152:155], v132
	ds_read_b128 v[156:159], v132 offset:1024
	ds_read_b128 v[160:163], v132 offset:2048
	ds_read_b128 v[164:167], v132 offset:3072
	s_cmp_eq_u32 s82, s72
	s_cselect_b32 s17, s51, s53
	s_cselect_b32 s16, s50, s52
	s_cselect_b32 s21, s15, s27
	s_cselect_b32 s20, s14, s26
	s_add_u32 s8, s26, 0xffffff80
	s_addc_u32 s9, s27, -1
	s_mov_b32 m0, s42
	s_mov_b64 s[18:19], s[8:9]
	ds_read_b128 v[168:171], v199 offset:8192
	ds_read_b128 v[172:175], v199 offset:9216
	ds_read_b128 v[176:179], v199 offset:10240
	ds_read_b128 v[180:183], v199 offset:11264
	ds_read_b128 v[184:187], v199 offset:12288
	ds_read_b128 v[188:191], v199 offset:13312
	ds_read_b128 v[202:205], v199 offset:14336
	ds_read_b128 v[206:209], v199 offset:15360
	s_add_u32 s8, s8, s54
	global_load_lds_dwordx4 v194, s[18:19]
	s_mov_b32 m0, s43
	s_addc_u32 s9, s9, s55
	global_load_lds_dwordx4 v195, s[18:19]
	s_mov_b32 m0, s44
	s_add_u32 s18, s16, 0x80
	global_load_lds_dwordx4 v194, s[8:9]
	s_mov_b32 m0, s45
	s_addc_u32 s19, s17, 0
	global_load_lds_dwordx4 v195, s[8:9]
	s_waitcnt vmcnt(8)
	s_waitcnt lgkmcnt(0)
	s_barrier
	s_waitcnt lgkmcnt(0)
	v_mfma_f32_16x16x32_bf16 v[4:7], v[136:139], v[168:171], v[4:7]
	v_mfma_f32_16x16x32_bf16 v[4:7], v[140:143], v[172:175], v[4:7]
	v_mfma_f32_16x16x32_bf16 v[8:11], v[144:147], v[168:171], v[8:11]
	v_mfma_f32_16x16x32_bf16 v[8:11], v[148:151], v[172:175], v[8:11]
	v_mfma_f32_16x16x32_bf16 v[12:15], v[136:139], v[176:179], v[12:15]
	v_mfma_f32_16x16x32_bf16 v[12:15], v[140:143], v[180:183], v[12:15]
	v_mfma_f32_16x16x32_bf16 v[16:19], v[144:147], v[176:179], v[16:19]
	v_mfma_f32_16x16x32_bf16 v[16:19], v[148:151], v[180:183], v[16:19]
	v_mfma_f32_16x16x32_bf16 v[20:23], v[136:139], v[184:187], v[20:23]
	v_mfma_f32_16x16x32_bf16 v[20:23], v[140:143], v[188:191], v[20:23]
	v_mfma_f32_16x16x32_bf16 v[24:27], v[144:147], v[184:187], v[24:27]
	v_mfma_f32_16x16x32_bf16 v[24:27], v[148:151], v[188:191], v[24:27]
	v_mfma_f32_16x16x32_bf16 v[28:31], v[136:139], v[202:205], v[28:31]
	v_mfma_f32_16x16x32_bf16 v[28:31], v[140:143], v[206:209], v[28:31]
	v_mfma_f32_16x16x32_bf16 v[32:35], v[144:147], v[202:205], v[32:35]
	v_mfma_f32_16x16x32_bf16 v[32:35], v[148:151], v[206:209], v[32:35]
	v_mfma_f32_16x16x32_bf16 v[36:39], v[152:155], v[168:171], v[36:39]
	v_mfma_f32_16x16x32_bf16 v[36:39], v[156:159], v[172:175], v[36:39]
	v_mfma_f32_16x16x32_bf16 v[40:43], v[160:163], v[168:171], v[40:43]
	v_mfma_f32_16x16x32_bf16 v[40:43], v[164:167], v[172:175], v[40:43]
	v_mfma_f32_16x16x32_bf16 v[44:47], v[152:155], v[176:179], v[44:47]
	v_mfma_f32_16x16x32_bf16 v[44:47], v[156:159], v[180:183], v[44:47]
	v_mfma_f32_16x16x32_bf16 v[48:51], v[160:163], v[176:179], v[48:51]
	v_mfma_f32_16x16x32_bf16 v[48:51], v[164:167], v[180:183], v[48:51]
	v_mfma_f32_16x16x32_bf16 v[52:55], v[152:155], v[184:187], v[52:55]
	v_mfma_f32_16x16x32_bf16 v[52:55], v[156:159], v[188:191], v[52:55]
	v_mfma_f32_16x16x32_bf16 v[56:59], v[160:163], v[184:187], v[56:59]
	v_mfma_f32_16x16x32_bf16 v[56:59], v[164:167], v[188:191], v[56:59]
	v_mfma_f32_16x16x32_bf16 v[60:63], v[152:155], v[202:205], v[60:63]
	v_mfma_f32_16x16x32_bf16 v[60:63], v[156:159], v[206:209], v[60:63]
	v_mfma_f32_16x16x32_bf16 v[64:67], v[160:163], v[202:205], v[64:67]
	v_mfma_f32_16x16x32_bf16 v[64:67], v[164:167], v[206:209], v[64:67]
	s_barrier
	s_mov_b32 m0, s46
	s_mov_b64 s[8:9], s[16:17]
	ds_read_b128 v[168:171], v199 offset:24576
	ds_read_b128 v[172:175], v199 offset:25600
	ds_read_b128 v[176:179], v199 offset:26624
	ds_read_b128 v[180:183], v199 offset:27648
	ds_read_b128 v[184:187], v199 offset:28672
	ds_read_b128 v[188:191], v199 offset:29696
	ds_read_b128 v[202:205], v199 offset:30720
	ds_read_b128 v[206:209], v199 offset:31744
	s_nop 0
	global_load_lds_dwordx4 v201, s[8:9]
	s_mov_b32 m0, s47
	s_nop 0
	global_load_lds_dwordx4 v200, s[8:9]
	s_add_u32 s8, s16, s54
	s_addc_u32 s9, s17, s55
	s_mov_b32 m0, s30
	s_nop 0
	global_load_lds_dwordx4 v201, s[8:9]
	s_mov_b32 m0, s31
	s_nop 0
	global_load_lds_dwordx4 v200, s[8:9]
	s_waitcnt vmcnt(6)
	s_waitcnt lgkmcnt(0)
	s_barrier
	s_waitcnt lgkmcnt(0)
	v_mfma_f32_16x16x32_bf16 v[68:71], v[136:139], v[168:171], v[68:71]
	v_mfma_f32_16x16x32_bf16 v[68:71], v[140:143], v[172:175], v[68:71]
	v_mfma_f32_16x16x32_bf16 v[72:75], v[144:147], v[168:171], v[72:75]
	v_mfma_f32_16x16x32_bf16 v[72:75], v[148:151], v[172:175], v[72:75]
	v_mfma_f32_16x16x32_bf16 v[76:79], v[136:139], v[176:179], v[76:79]
	v_mfma_f32_16x16x32_bf16 v[76:79], v[140:143], v[180:183], v[76:79]
	v_mfma_f32_16x16x32_bf16 v[80:83], v[144:147], v[176:179], v[80:83]
	v_mfma_f32_16x16x32_bf16 v[80:83], v[148:151], v[180:183], v[80:83]
	v_mfma_f32_16x16x32_bf16 v[84:87], v[136:139], v[184:187], v[84:87]
	v_mfma_f32_16x16x32_bf16 v[84:87], v[140:143], v[188:191], v[84:87]
	v_mfma_f32_16x16x32_bf16 v[88:91], v[144:147], v[184:187], v[88:91]
	v_mfma_f32_16x16x32_bf16 v[88:91], v[148:151], v[188:191], v[88:91]
	v_mfma_f32_16x16x32_bf16 v[92:95], v[136:139], v[202:205], v[92:95]
	v_mfma_f32_16x16x32_bf16 v[92:95], v[140:143], v[206:209], v[92:95]
	v_mfma_f32_16x16x32_bf16 v[96:99], v[144:147], v[202:205], v[96:99]
	v_mfma_f32_16x16x32_bf16 v[96:99], v[148:151], v[206:209], v[96:99]
	v_mfma_f32_16x16x32_bf16 v[100:103], v[152:155], v[168:171], v[100:103]
	v_mfma_f32_16x16x32_bf16 v[100:103], v[156:159], v[172:175], v[100:103]
	v_mfma_f32_16x16x32_bf16 v[104:107], v[160:163], v[168:171], v[104:107]
	v_mfma_f32_16x16x32_bf16 v[104:107], v[164:167], v[172:175], v[104:107]
	v_mfma_f32_16x16x32_bf16 v[108:111], v[152:155], v[176:179], v[108:111]
	v_mfma_f32_16x16x32_bf16 v[108:111], v[156:159], v[180:183], v[108:111]
	v_mfma_f32_16x16x32_bf16 v[112:115], v[160:163], v[176:179], v[112:115]
	v_mfma_f32_16x16x32_bf16 v[112:115], v[164:167], v[180:183], v[112:115]
	v_mfma_f32_16x16x32_bf16 v[116:119], v[152:155], v[184:187], v[116:119]
	v_mfma_f32_16x16x32_bf16 v[116:119], v[156:159], v[188:191], v[116:119]
	v_mfma_f32_16x16x32_bf16 v[120:123], v[160:163], v[184:187], v[120:123]
	v_mfma_f32_16x16x32_bf16 v[120:123], v[164:167], v[188:191], v[120:123]
	v_mfma_f32_16x16x32_bf16 v[124:127], v[152:155], v[202:205], v[124:127]
	v_mfma_f32_16x16x32_bf16 v[124:127], v[156:159], v[206:209], v[124:127]
	v_mfma_f32_16x16x32_bf16 v[128:131], v[160:163], v[202:205], v[128:131]
	v_mfma_f32_16x16x32_bf16 v[128:131], v[164:167], v[206:209], v[128:131]
	s_barrier
	ds_read_b128 v[136:139], v133
	ds_read_b128 v[140:143], v133 offset:1024
	ds_read_b128 v[144:147], v133 offset:2048
	ds_read_b128 v[148:151], v133 offset:3072
	ds_read_b128 v[152:155], v134
	ds_read_b128 v[156:159], v134 offset:1024
	ds_read_b128 v[160:163], v134 offset:2048
	ds_read_b128 v[164:167], v134 offset:3072
	s_mov_b32 m0, s85
	s_mov_b64 s[8:9], s[20:21]
	ds_read_b128 v[168:171], v199 offset:40960
	ds_read_b128 v[172:175], v199 offset:41984
	ds_read_b128 v[176:179], v199 offset:43008
	ds_read_b128 v[180:183], v199 offset:44032
	ds_read_b128 v[184:187], v199 offset:45056
	ds_read_b128 v[188:191], v199 offset:46080
	ds_read_b128 v[202:205], v199 offset:47104
	ds_read_b128 v[206:209], v199 offset:48128
	s_nop 0
	global_load_lds_dwordx4 v194, s[8:9]
	s_mov_b32 m0, s86
	s_nop 0
	global_load_lds_dwordx4 v195, s[8:9]
	s_add_u32 s8, s20, s54
	s_addc_u32 s9, s21, s55
	s_mov_b32 m0, s87
	s_nop 0
	global_load_lds_dwordx4 v194, s[8:9]
	s_mov_b32 m0, s88
	s_nop 0
	global_load_lds_dwordx4 v195, s[8:9]
	s_waitcnt vmcnt(8)
	s_waitcnt lgkmcnt(0)
	s_barrier
	s_waitcnt lgkmcnt(0)
	v_mfma_f32_16x16x32_bf16 v[4:7], v[136:139], v[168:171], v[4:7]
	v_mfma_f32_16x16x32_bf16 v[4:7], v[140:143], v[172:175], v[4:7]
	v_mfma_f32_16x16x32_bf16 v[8:11], v[144:147], v[168:171], v[8:11]
	v_mfma_f32_16x16x32_bf16 v[8:11], v[148:151], v[172:175], v[8:11]
	v_mfma_f32_16x16x32_bf16 v[12:15], v[136:139], v[176:179], v[12:15]
	v_mfma_f32_16x16x32_bf16 v[12:15], v[140:143], v[180:183], v[12:15]
	v_mfma_f32_16x16x32_bf16 v[16:19], v[144:147], v[176:179], v[16:19]
	v_mfma_f32_16x16x32_bf16 v[16:19], v[148:151], v[180:183], v[16:19]
	v_mfma_f32_16x16x32_bf16 v[20:23], v[136:139], v[184:187], v[20:23]
	v_mfma_f32_16x16x32_bf16 v[20:23], v[140:143], v[188:191], v[20:23]
	v_mfma_f32_16x16x32_bf16 v[24:27], v[144:147], v[184:187], v[24:27]
	v_mfma_f32_16x16x32_bf16 v[24:27], v[148:151], v[188:191], v[24:27]
	v_mfma_f32_16x16x32_bf16 v[28:31], v[136:139], v[202:205], v[28:31]
	v_mfma_f32_16x16x32_bf16 v[28:31], v[140:143], v[206:209], v[28:31]
	v_mfma_f32_16x16x32_bf16 v[32:35], v[144:147], v[202:205], v[32:35]
	v_mfma_f32_16x16x32_bf16 v[32:35], v[148:151], v[206:209], v[32:35]
	v_mfma_f32_16x16x32_bf16 v[36:39], v[152:155], v[168:171], v[36:39]
	v_mfma_f32_16x16x32_bf16 v[36:39], v[156:159], v[172:175], v[36:39]
	v_mfma_f32_16x16x32_bf16 v[40:43], v[160:163], v[168:171], v[40:43]
	v_mfma_f32_16x16x32_bf16 v[40:43], v[164:167], v[172:175], v[40:43]
	v_mfma_f32_16x16x32_bf16 v[44:47], v[152:155], v[176:179], v[44:47]
	v_mfma_f32_16x16x32_bf16 v[44:47], v[156:159], v[180:183], v[44:47]
	v_mfma_f32_16x16x32_bf16 v[48:51], v[160:163], v[176:179], v[48:51]
	v_mfma_f32_16x16x32_bf16 v[48:51], v[164:167], v[180:183], v[48:51]
	v_mfma_f32_16x16x32_bf16 v[52:55], v[152:155], v[184:187], v[52:55]
	v_mfma_f32_16x16x32_bf16 v[52:55], v[156:159], v[188:191], v[52:55]
	v_mfma_f32_16x16x32_bf16 v[56:59], v[160:163], v[184:187], v[56:59]
	v_mfma_f32_16x16x32_bf16 v[56:59], v[164:167], v[188:191], v[56:59]
	v_mfma_f32_16x16x32_bf16 v[60:63], v[152:155], v[202:205], v[60:63]
	v_mfma_f32_16x16x32_bf16 v[60:63], v[156:159], v[206:209], v[60:63]
	v_mfma_f32_16x16x32_bf16 v[64:67], v[160:163], v[202:205], v[64:67]
	v_mfma_f32_16x16x32_bf16 v[64:67], v[164:167], v[206:209], v[64:67]
	s_barrier
	s_mov_b32 m0, s48
	s_mov_b64 s[8:9], s[18:19]
	ds_read_b128 v[168:171], v199 offset:57344
	ds_read_b128 v[172:175], v199 offset:58368
	ds_read_b128 v[176:179], v199 offset:59392
	ds_read_b128 v[180:183], v199 offset:60416
	ds_read_b128 v[184:187], v199 offset:61440
	ds_read_b128 v[188:191], v199 offset:62464
	ds_read_b128 v[202:205], v199 offset:63488
	ds_read_b128 v[206:209], v199 offset:64512
	s_nop 0
	global_load_lds_dwordx4 v201, s[8:9]
	s_mov_b32 m0, s49
	s_nop 0
	global_load_lds_dwordx4 v200, s[8:9]
	s_add_u32 s8, s18, s54
	s_addc_u32 s9, s19, s55
	s_mov_b32 m0, s28
	s_nop 0
	global_load_lds_dwordx4 v201, s[8:9]
	s_mov_b32 m0, s29
	s_nop 0
	global_load_lds_dwordx4 v200, s[8:9]
	s_waitcnt vmcnt(6)
	s_waitcnt lgkmcnt(0)
	s_barrier
	s_waitcnt lgkmcnt(0)
	v_mfma_f32_16x16x32_bf16 v[68:71], v[136:139], v[168:171], v[68:71]
	v_mfma_f32_16x16x32_bf16 v[68:71], v[140:143], v[172:175], v[68:71]
	v_mfma_f32_16x16x32_bf16 v[72:75], v[144:147], v[168:171], v[72:75]
	v_mfma_f32_16x16x32_bf16 v[72:75], v[148:151], v[172:175], v[72:75]
	v_mfma_f32_16x16x32_bf16 v[76:79], v[136:139], v[176:179], v[76:79]
	v_mfma_f32_16x16x32_bf16 v[76:79], v[140:143], v[180:183], v[76:79]
	v_mfma_f32_16x16x32_bf16 v[80:83], v[144:147], v[176:179], v[80:83]
	v_mfma_f32_16x16x32_bf16 v[80:83], v[148:151], v[180:183], v[80:83]
	v_mfma_f32_16x16x32_bf16 v[84:87], v[136:139], v[184:187], v[84:87]
	v_mfma_f32_16x16x32_bf16 v[84:87], v[140:143], v[188:191], v[84:87]
	v_mfma_f32_16x16x32_bf16 v[88:91], v[144:147], v[184:187], v[88:91]
	v_mfma_f32_16x16x32_bf16 v[88:91], v[148:151], v[188:191], v[88:91]
	v_mfma_f32_16x16x32_bf16 v[92:95], v[136:139], v[202:205], v[92:95]
	v_mfma_f32_16x16x32_bf16 v[92:95], v[140:143], v[206:209], v[92:95]
	v_mfma_f32_16x16x32_bf16 v[96:99], v[144:147], v[202:205], v[96:99]
	v_mfma_f32_16x16x32_bf16 v[96:99], v[148:151], v[206:209], v[96:99]
	v_mfma_f32_16x16x32_bf16 v[100:103], v[152:155], v[168:171], v[100:103]
	v_mfma_f32_16x16x32_bf16 v[100:103], v[156:159], v[172:175], v[100:103]
	v_mfma_f32_16x16x32_bf16 v[104:107], v[160:163], v[168:171], v[104:107]
	v_mfma_f32_16x16x32_bf16 v[104:107], v[164:167], v[172:175], v[104:107]
	v_mfma_f32_16x16x32_bf16 v[108:111], v[152:155], v[176:179], v[108:111]
	v_mfma_f32_16x16x32_bf16 v[108:111], v[156:159], v[180:183], v[108:111]
	v_mfma_f32_16x16x32_bf16 v[112:115], v[160:163], v[176:179], v[112:115]
	v_mfma_f32_16x16x32_bf16 v[112:115], v[164:167], v[180:183], v[112:115]
	v_mfma_f32_16x16x32_bf16 v[116:119], v[152:155], v[184:187], v[116:119]
	v_mfma_f32_16x16x32_bf16 v[116:119], v[156:159], v[188:191], v[116:119]
	v_mfma_f32_16x16x32_bf16 v[120:123], v[160:163], v[184:187], v[120:123]
	v_mfma_f32_16x16x32_bf16 v[120:123], v[164:167], v[188:191], v[120:123]
	v_mfma_f32_16x16x32_bf16 v[124:127], v[152:155], v[202:205], v[124:127]
	v_mfma_f32_16x16x32_bf16 v[124:127], v[156:159], v[206:209], v[124:127]
	v_mfma_f32_16x16x32_bf16 v[128:131], v[160:163], v[202:205], v[128:131]
	v_mfma_f32_16x16x32_bf16 v[128:131], v[164:167], v[206:209], v[128:131]
	s_barrier
	s_add_i32 s8, s72, 2
	s_add_u32 s52, s52, 0x100
	s_addc_u32 s53, s53, 0
	s_add_u32 s26, s26, 0x100
	s_addc_u32 s27, s27, 0
	s_cmp_ge_i32 s72, s82
	s_mov_b32 s72, s8
	s_cbranch_scc0 .LBB0_287

.LBB0_429:
	ds_read_b128 v[136:139], v2
	ds_read_b128 v[140:143], v2 offset:1024
	ds_read_b128 v[144:147], v2 offset:2048
	ds_read_b128 v[148:151], v2 offset:3072
	ds_read_b128 v[152:155], v132
	ds_read_b128 v[156:159], v132 offset:1024
	ds_read_b128 v[160:163], v132 offset:2048
	ds_read_b128 v[164:167], v132 offset:3072
	s_cmp_eq_u32 s73, s66
	s_cselect_b32 s17, s51, s49
	s_cselect_b32 s16, s50, s48
	s_cselect_b32 s21, s15, s27
	s_cselect_b32 s20, s14, s26
	s_add_u32 s18, s26, 0xffffff80
	s_addc_u32 s19, s27, -1
	s_mov_b32 m0, s40
	s_mov_b64 s[96:97], s[18:19]
	ds_read_b128 v[168:171], v199
	ds_read_b128 v[172:175], v199 offset:1024
	ds_read_b128 v[176:179], v199 offset:2048
	ds_read_b128 v[180:183], v199 offset:3072
	ds_read_b128 v[184:187], v199 offset:4096
	ds_read_b128 v[188:191], v199 offset:5120
	ds_read_b128 v[202:205], v199 offset:6144
	ds_read_b128 v[206:209], v199 offset:7168
	s_add_u32 s18, s18, s52
	global_load_lds_dwordx4 v194, s[96:97]
	s_mov_b32 m0, s41
	s_addc_u32 s19, s19, s53
	global_load_lds_dwordx4 v195, s[96:97]
	s_mov_b32 m0, s42
	s_nop 0
	global_load_lds_dwordx4 v194, s[18:19]
	s_mov_b32 m0, s43
	s_nop 0
	global_load_lds_dwordx4 v195, s[18:19]
	s_waitcnt vmcnt(8)
	s_waitcnt lgkmcnt(0)
	s_add_u32 s18, s16, 0x80
	s_addc_u32 s19, s17, 0
	s_barrier
	s_waitcnt lgkmcnt(0)
	v_mfma_f32_16x16x32_bf16 v[4:7], v[136:139], v[168:171], v[4:7]
	v_mfma_f32_16x16x32_bf16 v[4:7], v[140:143], v[172:175], v[4:7]
	v_mfma_f32_16x16x32_bf16 v[8:11], v[144:147], v[168:171], v[8:11]
	v_mfma_f32_16x16x32_bf16 v[8:11], v[148:151], v[172:175], v[8:11]
	v_mfma_f32_16x16x32_bf16 v[12:15], v[136:139], v[176:179], v[12:15]
	v_mfma_f32_16x16x32_bf16 v[12:15], v[140:143], v[180:183], v[12:15]
	v_mfma_f32_16x16x32_bf16 v[16:19], v[144:147], v[176:179], v[16:19]
	v_mfma_f32_16x16x32_bf16 v[16:19], v[148:151], v[180:183], v[16:19]
	v_mfma_f32_16x16x32_bf16 v[20:23], v[136:139], v[184:187], v[20:23]
	v_mfma_f32_16x16x32_bf16 v[20:23], v[140:143], v[188:191], v[20:23]
	v_mfma_f32_16x16x32_bf16 v[24:27], v[144:147], v[184:187], v[24:27]
	v_mfma_f32_16x16x32_bf16 v[24:27], v[148:151], v[188:191], v[24:27]
	v_mfma_f32_16x16x32_bf16 v[28:31], v[136:139], v[202:205], v[28:31]
	v_mfma_f32_16x16x32_bf16 v[28:31], v[140:143], v[206:209], v[28:31]
	v_mfma_f32_16x16x32_bf16 v[32:35], v[144:147], v[202:205], v[32:35]
	v_mfma_f32_16x16x32_bf16 v[32:35], v[148:151], v[206:209], v[32:35]
	v_mfma_f32_16x16x32_bf16 v[36:39], v[152:155], v[168:171], v[36:39]
	v_mfma_f32_16x16x32_bf16 v[36:39], v[156:159], v[172:175], v[36:39]
	v_mfma_f32_16x16x32_bf16 v[40:43], v[160:163], v[168:171], v[40:43]
	v_mfma_f32_16x16x32_bf16 v[40:43], v[164:167], v[172:175], v[40:43]
	v_mfma_f32_16x16x32_bf16 v[44:47], v[152:155], v[176:179], v[44:47]
	v_mfma_f32_16x16x32_bf16 v[44:47], v[156:159], v[180:183], v[44:47]
	v_mfma_f32_16x16x32_bf16 v[48:51], v[160:163], v[176:179], v[48:51]
	v_mfma_f32_16x16x32_bf16 v[48:51], v[164:167], v[180:183], v[48:51]
	v_mfma_f32_16x16x32_bf16 v[52:55], v[152:155], v[184:187], v[52:55]
	v_mfma_f32_16x16x32_bf16 v[52:55], v[156:159], v[188:191], v[52:55]
	v_mfma_f32_16x16x32_bf16 v[56:59], v[160:163], v[184:187], v[56:59]
	v_mfma_f32_16x16x32_bf16 v[56:59], v[164:167], v[188:191], v[56:59]
	v_mfma_f32_16x16x32_bf16 v[60:63], v[152:155], v[202:205], v[60:63]
	v_mfma_f32_16x16x32_bf16 v[60:63], v[156:159], v[206:209], v[60:63]
	v_mfma_f32_16x16x32_bf16 v[64:67], v[160:163], v[202:205], v[64:67]
	v_mfma_f32_16x16x32_bf16 v[64:67], v[164:167], v[206:209], v[64:67]
	s_barrier
	s_mov_b32 m0, s44
	s_mov_b64 s[96:97], s[16:17]
	ds_read_b128 v[168:171], v199 offset:16384
	ds_read_b128 v[172:175], v199 offset:17408
	ds_read_b128 v[176:179], v199 offset:18432
	ds_read_b128 v[180:183], v199 offset:19456
	ds_read_b128 v[184:187], v199 offset:20480
	ds_read_b128 v[188:191], v199 offset:21504
	ds_read_b128 v[202:205], v199 offset:22528
	ds_read_b128 v[206:209], v199 offset:23552
	s_add_u32 s16, s16, s52
	global_load_lds_dwordx4 v201, s[96:97]
	s_mov_b32 m0, s45
	s_addc_u32 s17, s17, s53
	global_load_lds_dwordx4 v200, s[96:97]
	s_mov_b32 m0, s30
	s_nop 0
	global_load_lds_dwordx4 v201, s[16:17]
	s_mov_b32 m0, s31
	s_nop 0
	global_load_lds_dwordx4 v200, s[16:17]
	s_waitcnt vmcnt(6)
	s_waitcnt lgkmcnt(0)
	s_barrier
	s_waitcnt lgkmcnt(0)
	v_mfma_f32_16x16x32_bf16 v[68:71], v[136:139], v[168:171], v[68:71]
	v_mfma_f32_16x16x32_bf16 v[68:71], v[140:143], v[172:175], v[68:71]
	v_mfma_f32_16x16x32_bf16 v[72:75], v[144:147], v[168:171], v[72:75]
	v_mfma_f32_16x16x32_bf16 v[72:75], v[148:151], v[172:175], v[72:75]
	v_mfma_f32_16x16x32_bf16 v[76:79], v[136:139], v[176:179], v[76:79]
	v_mfma_f32_16x16x32_bf16 v[76:79], v[140:143], v[180:183], v[76:79]
	v_mfma_f32_16x16x32_bf16 v[80:83], v[144:147], v[176:179], v[80:83]
	v_mfma_f32_16x16x32_bf16 v[80:83], v[148:151], v[180:183], v[80:83]
	v_mfma_f32_16x16x32_bf16 v[84:87], v[136:139], v[184:187], v[84:87]
	v_mfma_f32_16x16x32_bf16 v[84:87], v[140:143], v[188:191], v[84:87]
	v_mfma_f32_16x16x32_bf16 v[88:91], v[144:147], v[184:187], v[88:91]
	v_mfma_f32_16x16x32_bf16 v[88:91], v[148:151], v[188:191], v[88:91]
	v_mfma_f32_16x16x32_bf16 v[92:95], v[136:139], v[202:205], v[92:95]
	v_mfma_f32_16x16x32_bf16 v[92:95], v[140:143], v[206:209], v[92:95]
	v_mfma_f32_16x16x32_bf16 v[96:99], v[144:147], v[202:205], v[96:99]
	v_mfma_f32_16x16x32_bf16 v[96:99], v[148:151], v[206:209], v[96:99]
	v_mfma_f32_16x16x32_bf16 v[100:103], v[152:155], v[168:171], v[100:103]
	v_mfma_f32_16x16x32_bf16 v[100:103], v[156:159], v[172:175], v[100:103]
	v_mfma_f32_16x16x32_bf16 v[104:107], v[160:163], v[168:171], v[104:107]
	v_mfma_f32_16x16x32_bf16 v[104:107], v[164:167], v[172:175], v[104:107]
	v_mfma_f32_16x16x32_bf16 v[108:111], v[152:155], v[176:179], v[108:111]
	v_mfma_f32_16x16x32_bf16 v[108:111], v[156:159], v[180:183], v[108:111]
	v_mfma_f32_16x16x32_bf16 v[112:115], v[160:163], v[176:179], v[112:115]
	v_mfma_f32_16x16x32_bf16 v[112:115], v[164:167], v[180:183], v[112:115]
	v_mfma_f32_16x16x32_bf16 v[116:119], v[152:155], v[184:187], v[116:119]
	v_mfma_f32_16x16x32_bf16 v[116:119], v[156:159], v[188:191], v[116:119]
	v_mfma_f32_16x16x32_bf16 v[120:123], v[160:163], v[184:187], v[120:123]
	v_mfma_f32_16x16x32_bf16 v[120:123], v[164:167], v[188:191], v[120:123]
	v_mfma_f32_16x16x32_bf16 v[124:127], v[152:155], v[202:205], v[124:127]
	v_mfma_f32_16x16x32_bf16 v[124:127], v[156:159], v[206:209], v[124:127]
	v_mfma_f32_16x16x32_bf16 v[128:131], v[160:163], v[202:205], v[128:131]
	v_mfma_f32_16x16x32_bf16 v[128:131], v[164:167], v[206:209], v[128:131]
	s_barrier
	ds_read_b128 v[136:139], v133
	ds_read_b128 v[140:143], v133 offset:1024
	ds_read_b128 v[144:147], v133 offset:2048
	ds_read_b128 v[148:151], v133 offset:3072
	ds_read_b128 v[152:155], v134
	ds_read_b128 v[156:159], v134 offset:1024
	ds_read_b128 v[160:163], v134 offset:2048
	ds_read_b128 v[164:167], v134 offset:3072
	s_mov_b32 m0, s84
	s_mov_b64 s[16:17], s[20:21]
	ds_read_b128 v[168:171], v199 offset:32768
	ds_read_b128 v[172:175], v199 offset:33792
	ds_read_b128 v[176:179], v199 offset:34816
	ds_read_b128 v[180:183], v199 offset:35840
	ds_read_b128 v[184:187], v199 offset:36864
	ds_read_b128 v[188:191], v199 offset:37888
	ds_read_b128 v[202:205], v199 offset:38912
	ds_read_b128 v[206:209], v199 offset:39936
	s_nop 0
	global_load_lds_dwordx4 v194, s[16:17]
	s_mov_b32 m0, s85
	s_nop 0
	global_load_lds_dwordx4 v195, s[16:17]
	s_add_u32 s16, s20, s52
	s_addc_u32 s17, s21, s53
	s_mov_b32 m0, s86
	s_nop 0
	global_load_lds_dwordx4 v194, s[16:17]
	s_mov_b32 m0, s87
	s_nop 0
	global_load_lds_dwordx4 v195, s[16:17]
	s_waitcnt vmcnt(8)
	s_waitcnt lgkmcnt(0)
	s_barrier
	s_waitcnt lgkmcnt(0)
	v_mfma_f32_16x16x32_bf16 v[4:7], v[136:139], v[168:171], v[4:7]
	v_mfma_f32_16x16x32_bf16 v[4:7], v[140:143], v[172:175], v[4:7]
	v_mfma_f32_16x16x32_bf16 v[8:11], v[144:147], v[168:171], v[8:11]
	v_mfma_f32_16x16x32_bf16 v[8:11], v[148:151], v[172:175], v[8:11]
	v_mfma_f32_16x16x32_bf16 v[12:15], v[136:139], v[176:179], v[12:15]
	v_mfma_f32_16x16x32_bf16 v[12:15], v[140:143], v[180:183], v[12:15]
	v_mfma_f32_16x16x32_bf16 v[16:19], v[144:147], v[176:179], v[16:19]
	v_mfma_f32_16x16x32_bf16 v[16:19], v[148:151], v[180:183], v[16:19]
	v_mfma_f32_16x16x32_bf16 v[20:23], v[136:139], v[184:187], v[20:23]
	v_mfma_f32_16x16x32_bf16 v[20:23], v[140:143], v[188:191], v[20:23]
	v_mfma_f32_16x16x32_bf16 v[24:27], v[144:147], v[184:187], v[24:27]
	v_mfma_f32_16x16x32_bf16 v[24:27], v[148:151], v[188:191], v[24:27]
	v_mfma_f32_16x16x32_bf16 v[28:31], v[136:139], v[202:205], v[28:31]
	v_mfma_f32_16x16x32_bf16 v[28:31], v[140:143], v[206:209], v[28:31]
	v_mfma_f32_16x16x32_bf16 v[32:35], v[144:147], v[202:205], v[32:35]
	v_mfma_f32_16x16x32_bf16 v[32:35], v[148:151], v[206:209], v[32:35]
	v_mfma_f32_16x16x32_bf16 v[36:39], v[152:155], v[168:171], v[36:39]
	v_mfma_f32_16x16x32_bf16 v[36:39], v[156:159], v[172:175], v[36:39]
	v_mfma_f32_16x16x32_bf16 v[40:43], v[160:163], v[168:171], v[40:43]
	v_mfma_f32_16x16x32_bf16 v[40:43], v[164:167], v[172:175], v[40:43]
	v_mfma_f32_16x16x32_bf16 v[44:47], v[152:155], v[176:179], v[44:47]
	v_mfma_f32_16x16x32_bf16 v[44:47], v[156:159], v[180:183], v[44:47]
	v_mfma_f32_16x16x32_bf16 v[48:51], v[160:163], v[176:179], v[48:51]
	v_mfma_f32_16x16x32_bf16 v[48:51], v[164:167], v[180:183], v[48:51]
	v_mfma_f32_16x16x32_bf16 v[52:55], v[152:155], v[184:187], v[52:55]
	v_mfma_f32_16x16x32_bf16 v[52:55], v[156:159], v[188:191], v[52:55]
	v_mfma_f32_16x16x32_bf16 v[56:59], v[160:163], v[184:187], v[56:59]
	v_mfma_f32_16x16x32_bf16 v[56:59], v[164:167], v[188:191], v[56:59]
	v_mfma_f32_16x16x32_bf16 v[60:63], v[152:155], v[202:205], v[60:63]
	v_mfma_f32_16x16x32_bf16 v[60:63], v[156:159], v[206:209], v[60:63]
	v_mfma_f32_16x16x32_bf16 v[64:67], v[160:163], v[202:205], v[64:67]
	v_mfma_f32_16x16x32_bf16 v[64:67], v[164:167], v[206:209], v[64:67]
	s_barrier
	s_mov_b32 m0, s46
	s_mov_b64 s[16:17], s[18:19]
	ds_read_b128 v[168:171], v199 offset:49152
	ds_read_b128 v[172:175], v199 offset:50176
	ds_read_b128 v[176:179], v199 offset:51200
	ds_read_b128 v[180:183], v199 offset:52224
	ds_read_b128 v[184:187], v199 offset:53248
	ds_read_b128 v[188:191], v199 offset:54272
	ds_read_b128 v[202:205], v199 offset:55296
	ds_read_b128 v[206:209], v199 offset:56320
	s_nop 0
	global_load_lds_dwordx4 v201, s[16:17]
	s_mov_b32 m0, s47
	s_nop 0
	global_load_lds_dwordx4 v200, s[16:17]
	s_add_u32 s16, s18, s52
	s_addc_u32 s17, s19, s53
	s_mov_b32 m0, s28
	s_nop 0
	global_load_lds_dwordx4 v201, s[16:17]
	s_mov_b32 m0, s29
	s_nop 0
	global_load_lds_dwordx4 v200, s[16:17]
	s_waitcnt vmcnt(6)
	s_waitcnt lgkmcnt(0)
	s_barrier
	s_waitcnt lgkmcnt(0)
	v_mfma_f32_16x16x32_bf16 v[68:71], v[136:139], v[168:171], v[68:71]
	v_mfma_f32_16x16x32_bf16 v[68:71], v[140:143], v[172:175], v[68:71]
	v_mfma_f32_16x16x32_bf16 v[72:75], v[144:147], v[168:171], v[72:75]
	v_mfma_f32_16x16x32_bf16 v[72:75], v[148:151], v[172:175], v[72:75]
	v_mfma_f32_16x16x32_bf16 v[76:79], v[136:139], v[176:179], v[76:79]
	v_mfma_f32_16x16x32_bf16 v[76:79], v[140:143], v[180:183], v[76:79]
	v_mfma_f32_16x16x32_bf16 v[80:83], v[144:147], v[176:179], v[80:83]
	v_mfma_f32_16x16x32_bf16 v[80:83], v[148:151], v[180:183], v[80:83]
	v_mfma_f32_16x16x32_bf16 v[84:87], v[136:139], v[184:187], v[84:87]
	v_mfma_f32_16x16x32_bf16 v[84:87], v[140:143], v[188:191], v[84:87]
	v_mfma_f32_16x16x32_bf16 v[88:91], v[144:147], v[184:187], v[88:91]
	v_mfma_f32_16x16x32_bf16 v[88:91], v[148:151], v[188:191], v[88:91]
	v_mfma_f32_16x16x32_bf16 v[92:95], v[136:139], v[202:205], v[92:95]
	v_mfma_f32_16x16x32_bf16 v[92:95], v[140:143], v[206:209], v[92:95]
	v_mfma_f32_16x16x32_bf16 v[96:99], v[144:147], v[202:205], v[96:99]
	v_mfma_f32_16x16x32_bf16 v[96:99], v[148:151], v[206:209], v[96:99]
	v_mfma_f32_16x16x32_bf16 v[100:103], v[152:155], v[168:171], v[100:103]
	v_mfma_f32_16x16x32_bf16 v[100:103], v[156:159], v[172:175], v[100:103]
	v_mfma_f32_16x16x32_bf16 v[104:107], v[160:163], v[168:171], v[104:107]
	v_mfma_f32_16x16x32_bf16 v[104:107], v[164:167], v[172:175], v[104:107]
	v_mfma_f32_16x16x32_bf16 v[108:111], v[152:155], v[176:179], v[108:111]
	v_mfma_f32_16x16x32_bf16 v[108:111], v[156:159], v[180:183], v[108:111]
	v_mfma_f32_16x16x32_bf16 v[112:115], v[160:163], v[176:179], v[112:115]
	v_mfma_f32_16x16x32_bf16 v[112:115], v[164:167], v[180:183], v[112:115]
	v_mfma_f32_16x16x32_bf16 v[116:119], v[152:155], v[184:187], v[116:119]
	v_mfma_f32_16x16x32_bf16 v[116:119], v[156:159], v[188:191], v[116:119]
	v_mfma_f32_16x16x32_bf16 v[120:123], v[160:163], v[184:187], v[120:123]
	v_mfma_f32_16x16x32_bf16 v[120:123], v[164:167], v[188:191], v[120:123]
	v_mfma_f32_16x16x32_bf16 v[124:127], v[152:155], v[202:205], v[124:127]
	v_mfma_f32_16x16x32_bf16 v[124:127], v[156:159], v[206:209], v[124:127]
	v_mfma_f32_16x16x32_bf16 v[128:131], v[160:163], v[202:205], v[128:131]
	v_mfma_f32_16x16x32_bf16 v[128:131], v[164:167], v[206:209], v[128:131]
	s_barrier
	s_add_i32 s8, s66, 2
	s_add_u32 s48, s48, 0x100
	s_addc_u32 s49, s49, 0
	s_add_u32 s26, s26, 0x100
	s_addc_u32 s27, s27, 0
	s_cmp_ge_i32 s66, s73
	s_mov_b32 s66, s8
	s_cbranch_scc0 .LBB0_429
	v_readlane_b32 s96, v255, 41
	v_readlane_b32 s97, v255, 42

.LBB0_855:
	ds_read_b128 v[136:139], v132
	ds_read_b128 v[140:143], v132 offset:1024
	ds_read_b128 v[144:147], v132 offset:2048
	ds_read_b128 v[148:151], v132 offset:3072
	ds_read_b128 v[152:155], v133
	ds_read_b128 v[156:159], v133 offset:1024
	ds_read_b128 v[160:163], v133 offset:2048
	ds_read_b128 v[164:167], v133 offset:3072
	s_cmp_eq_u32 s4, s90
	s_cselect_b32 s17, s41, s89
	s_cselect_b32 s16, s40, s88
	s_cselect_b32 s21, s59, s27
	s_cselect_b32 s20, s58, s26
	s_add_u32 s8, s26, 0xffffff80
	s_addc_u32 s9, s27, -1
	s_mov_b32 m0, s80
	s_mov_b64 s[18:19], s[8:9]
	ds_read_b128 v[168:171], v246 offset:8192
	ds_read_b128 v[172:175], v246 offset:9216
	ds_read_b128 v[176:179], v246 offset:10240
	ds_read_b128 v[180:183], v246 offset:11264
	ds_read_b128 v[184:187], v246 offset:12288
	ds_read_b128 v[188:191], v246 offset:13312
	ds_read_b128 v[192:195], v246 offset:14336
	ds_read_b128 v[196:199], v246 offset:15360
	s_add_u32 s8, s8, s42
	global_load_lds_dwordx4 v242, s[18:19]
	s_mov_b32 m0, s81
	s_addc_u32 s9, s9, s43
	global_load_lds_dwordx4 v2, s[18:19]
	s_mov_b32 m0, s82
	s_add_u32 s18, s16, 0x80
	global_load_lds_dwordx4 v242, s[8:9]
	s_mov_b32 m0, s83
	s_addc_u32 s19, s17, 0
	global_load_lds_dwordx4 v2, s[8:9]
	s_waitcnt vmcnt(8)
	s_waitcnt lgkmcnt(0)
	s_barrier
	s_waitcnt lgkmcnt(0)
	v_mfma_f32_16x16x32_bf16 v[4:7], v[136:139], v[168:171], v[4:7]
	v_mfma_f32_16x16x32_bf16 v[4:7], v[140:143], v[172:175], v[4:7]
	v_mfma_f32_16x16x32_bf16 v[8:11], v[144:147], v[168:171], v[8:11]
	v_mfma_f32_16x16x32_bf16 v[8:11], v[148:151], v[172:175], v[8:11]
	v_mfma_f32_16x16x32_bf16 v[12:15], v[136:139], v[176:179], v[12:15]
	v_mfma_f32_16x16x32_bf16 v[12:15], v[140:143], v[180:183], v[12:15]
	v_mfma_f32_16x16x32_bf16 v[16:19], v[144:147], v[176:179], v[16:19]
	v_mfma_f32_16x16x32_bf16 v[16:19], v[148:151], v[180:183], v[16:19]
	v_mfma_f32_16x16x32_bf16 v[20:23], v[136:139], v[184:187], v[20:23]
	v_mfma_f32_16x16x32_bf16 v[20:23], v[140:143], v[188:191], v[20:23]
	v_mfma_f32_16x16x32_bf16 v[24:27], v[144:147], v[184:187], v[24:27]
	v_mfma_f32_16x16x32_bf16 v[24:27], v[148:151], v[188:191], v[24:27]
	v_mfma_f32_16x16x32_bf16 v[28:31], v[136:139], v[192:195], v[28:31]
	v_mfma_f32_16x16x32_bf16 v[28:31], v[140:143], v[196:199], v[28:31]
	v_mfma_f32_16x16x32_bf16 v[32:35], v[144:147], v[192:195], v[32:35]
	v_mfma_f32_16x16x32_bf16 v[32:35], v[148:151], v[196:199], v[32:35]
	v_mfma_f32_16x16x32_bf16 v[36:39], v[152:155], v[168:171], v[36:39]
	v_mfma_f32_16x16x32_bf16 v[36:39], v[156:159], v[172:175], v[36:39]
	v_mfma_f32_16x16x32_bf16 v[40:43], v[160:163], v[168:171], v[40:43]
	v_mfma_f32_16x16x32_bf16 v[40:43], v[164:167], v[172:175], v[40:43]
	v_mfma_f32_16x16x32_bf16 v[44:47], v[152:155], v[176:179], v[44:47]
	v_mfma_f32_16x16x32_bf16 v[44:47], v[156:159], v[180:183], v[44:47]
	v_mfma_f32_16x16x32_bf16 v[48:51], v[160:163], v[176:179], v[48:51]
	v_mfma_f32_16x16x32_bf16 v[48:51], v[164:167], v[180:183], v[48:51]
	v_mfma_f32_16x16x32_bf16 v[52:55], v[152:155], v[184:187], v[52:55]
	v_mfma_f32_16x16x32_bf16 v[52:55], v[156:159], v[188:191], v[52:55]
	v_mfma_f32_16x16x32_bf16 v[56:59], v[160:163], v[184:187], v[56:59]
	v_mfma_f32_16x16x32_bf16 v[56:59], v[164:167], v[188:191], v[56:59]
	v_mfma_f32_16x16x32_bf16 v[60:63], v[152:155], v[192:195], v[60:63]
	v_mfma_f32_16x16x32_bf16 v[60:63], v[156:159], v[196:199], v[60:63]
	v_mfma_f32_16x16x32_bf16 v[64:67], v[160:163], v[192:195], v[64:67]
	v_mfma_f32_16x16x32_bf16 v[64:67], v[164:167], v[196:199], v[64:67]
	s_barrier
	s_mov_b32 m0, s84
	s_mov_b64 s[8:9], s[16:17]
	ds_read_b128 v[168:171], v246 offset:24576
	ds_read_b128 v[172:175], v246 offset:25600
	ds_read_b128 v[176:179], v246 offset:26624
	ds_read_b128 v[180:183], v246 offset:27648
	ds_read_b128 v[184:187], v246 offset:28672
	ds_read_b128 v[188:191], v246 offset:29696
	ds_read_b128 v[192:195], v246 offset:30720
	ds_read_b128 v[196:199], v246 offset:31744
	s_nop 0
	global_load_lds_dwordx4 v248, s[8:9]
	s_mov_b32 m0, s85
	s_nop 0
	global_load_lds_dwordx4 v247, s[8:9]
	s_add_u32 s8, s16, s42
	s_addc_u32 s9, s17, s43
	s_mov_b32 m0, s30
	s_nop 0
	global_load_lds_dwordx4 v248, s[8:9]
	s_mov_b32 m0, s31
	s_nop 0
	global_load_lds_dwordx4 v247, s[8:9]
	s_waitcnt vmcnt(6)
	s_waitcnt lgkmcnt(0)
	s_barrier
	s_waitcnt lgkmcnt(0)
	v_mfma_f32_16x16x32_bf16 v[68:71], v[136:139], v[168:171], v[68:71]
	v_mfma_f32_16x16x32_bf16 v[68:71], v[140:143], v[172:175], v[68:71]
	v_mfma_f32_16x16x32_bf16 v[72:75], v[144:147], v[168:171], v[72:75]
	v_mfma_f32_16x16x32_bf16 v[72:75], v[148:151], v[172:175], v[72:75]
	v_mfma_f32_16x16x32_bf16 v[76:79], v[136:139], v[176:179], v[76:79]
	v_mfma_f32_16x16x32_bf16 v[76:79], v[140:143], v[180:183], v[76:79]
	v_mfma_f32_16x16x32_bf16 v[80:83], v[144:147], v[176:179], v[80:83]
	v_mfma_f32_16x16x32_bf16 v[80:83], v[148:151], v[180:183], v[80:83]
	v_mfma_f32_16x16x32_bf16 v[84:87], v[136:139], v[184:187], v[84:87]
	v_mfma_f32_16x16x32_bf16 v[84:87], v[140:143], v[188:191], v[84:87]
	v_mfma_f32_16x16x32_bf16 v[88:91], v[144:147], v[184:187], v[88:91]
	v_mfma_f32_16x16x32_bf16 v[88:91], v[148:151], v[188:191], v[88:91]
	v_mfma_f32_16x16x32_bf16 v[92:95], v[136:139], v[192:195], v[92:95]
	v_mfma_f32_16x16x32_bf16 v[92:95], v[140:143], v[196:199], v[92:95]
	v_mfma_f32_16x16x32_bf16 v[96:99], v[144:147], v[192:195], v[96:99]
	v_mfma_f32_16x16x32_bf16 v[96:99], v[148:151], v[196:199], v[96:99]
	v_mfma_f32_16x16x32_bf16 v[100:103], v[152:155], v[168:171], v[100:103]
	v_mfma_f32_16x16x32_bf16 v[100:103], v[156:159], v[172:175], v[100:103]
	v_mfma_f32_16x16x32_bf16 v[104:107], v[160:163], v[168:171], v[104:107]
	v_mfma_f32_16x16x32_bf16 v[104:107], v[164:167], v[172:175], v[104:107]
	v_mfma_f32_16x16x32_bf16 v[108:111], v[152:155], v[176:179], v[108:111]
	v_mfma_f32_16x16x32_bf16 v[108:111], v[156:159], v[180:183], v[108:111]
	v_mfma_f32_16x16x32_bf16 v[112:115], v[160:163], v[176:179], v[112:115]
	v_mfma_f32_16x16x32_bf16 v[112:115], v[164:167], v[180:183], v[112:115]
	v_mfma_f32_16x16x32_bf16 v[116:119], v[152:155], v[184:187], v[116:119]
	v_mfma_f32_16x16x32_bf16 v[116:119], v[156:159], v[188:191], v[116:119]
	v_mfma_f32_16x16x32_bf16 v[120:123], v[160:163], v[184:187], v[120:123]
	v_mfma_f32_16x16x32_bf16 v[120:123], v[164:167], v[188:191], v[120:123]
	v_mfma_f32_16x16x32_bf16 v[124:127], v[152:155], v[192:195], v[124:127]
	v_mfma_f32_16x16x32_bf16 v[124:127], v[156:159], v[196:199], v[124:127]
	v_mfma_f32_16x16x32_bf16 v[128:131], v[160:163], v[192:195], v[128:131]
	v_mfma_f32_16x16x32_bf16 v[128:131], v[164:167], v[196:199], v[128:131]
	s_barrier
	ds_read_b128 v[136:139], v134
	ds_read_b128 v[140:143], v134 offset:1024
	ds_read_b128 v[144:147], v134 offset:2048
	ds_read_b128 v[148:151], v134 offset:3072
	ds_read_b128 v[152:155], v135
	ds_read_b128 v[156:159], v135 offset:1024
	ds_read_b128 v[160:163], v135 offset:2048
	ds_read_b128 v[164:167], v135 offset:3072
	s_mov_b32 m0, s7
	s_mov_b64 s[8:9], s[20:21]
	ds_read_b128 v[168:171], v246 offset:40960
	ds_read_b128 v[172:175], v246 offset:41984
	ds_read_b128 v[176:179], v246 offset:43008
	ds_read_b128 v[180:183], v246 offset:44032
	ds_read_b128 v[184:187], v246 offset:45056
	ds_read_b128 v[188:191], v246 offset:46080
	ds_read_b128 v[192:195], v246 offset:47104
	ds_read_b128 v[196:199], v246 offset:48128
	s_nop 0
	global_load_lds_dwordx4 v242, s[8:9]
	s_mov_b32 m0, s69
	s_nop 0
	global_load_lds_dwordx4 v2, s[8:9]
	s_add_u32 s8, s20, s42
	s_addc_u32 s9, s21, s43
	s_mov_b32 m0, s72
	s_nop 0
	global_load_lds_dwordx4 v242, s[8:9]
	s_mov_b32 m0, s73
	s_nop 0
	global_load_lds_dwordx4 v2, s[8:9]
	s_waitcnt vmcnt(8)
	s_waitcnt lgkmcnt(0)
	s_barrier
	s_waitcnt lgkmcnt(0)
	v_mfma_f32_16x16x32_bf16 v[4:7], v[136:139], v[168:171], v[4:7]
	v_mfma_f32_16x16x32_bf16 v[4:7], v[140:143], v[172:175], v[4:7]
	v_mfma_f32_16x16x32_bf16 v[8:11], v[144:147], v[168:171], v[8:11]
	v_mfma_f32_16x16x32_bf16 v[8:11], v[148:151], v[172:175], v[8:11]
	v_mfma_f32_16x16x32_bf16 v[12:15], v[136:139], v[176:179], v[12:15]
	v_mfma_f32_16x16x32_bf16 v[12:15], v[140:143], v[180:183], v[12:15]
	v_mfma_f32_16x16x32_bf16 v[16:19], v[144:147], v[176:179], v[16:19]
	v_mfma_f32_16x16x32_bf16 v[16:19], v[148:151], v[180:183], v[16:19]
	v_mfma_f32_16x16x32_bf16 v[20:23], v[136:139], v[184:187], v[20:23]
	v_mfma_f32_16x16x32_bf16 v[20:23], v[140:143], v[188:191], v[20:23]
	v_mfma_f32_16x16x32_bf16 v[24:27], v[144:147], v[184:187], v[24:27]
	v_mfma_f32_16x16x32_bf16 v[24:27], v[148:151], v[188:191], v[24:27]
	v_mfma_f32_16x16x32_bf16 v[28:31], v[136:139], v[192:195], v[28:31]
	v_mfma_f32_16x16x32_bf16 v[28:31], v[140:143], v[196:199], v[28:31]
	v_mfma_f32_16x16x32_bf16 v[32:35], v[144:147], v[192:195], v[32:35]
	v_mfma_f32_16x16x32_bf16 v[32:35], v[148:151], v[196:199], v[32:35]
	v_mfma_f32_16x16x32_bf16 v[36:39], v[152:155], v[168:171], v[36:39]
	v_mfma_f32_16x16x32_bf16 v[36:39], v[156:159], v[172:175], v[36:39]
	v_mfma_f32_16x16x32_bf16 v[40:43], v[160:163], v[168:171], v[40:43]
	v_mfma_f32_16x16x32_bf16 v[40:43], v[164:167], v[172:175], v[40:43]
	v_mfma_f32_16x16x32_bf16 v[44:47], v[152:155], v[176:179], v[44:47]
	v_mfma_f32_16x16x32_bf16 v[44:47], v[156:159], v[180:183], v[44:47]
	v_mfma_f32_16x16x32_bf16 v[48:51], v[160:163], v[176:179], v[48:51]
	v_mfma_f32_16x16x32_bf16 v[48:51], v[164:167], v[180:183], v[48:51]
	v_mfma_f32_16x16x32_bf16 v[52:55], v[152:155], v[184:187], v[52:55]
	v_mfma_f32_16x16x32_bf16 v[52:55], v[156:159], v[188:191], v[52:55]
	v_mfma_f32_16x16x32_bf16 v[56:59], v[160:163], v[184:187], v[56:59]
	v_mfma_f32_16x16x32_bf16 v[56:59], v[164:167], v[188:191], v[56:59]
	v_mfma_f32_16x16x32_bf16 v[60:63], v[152:155], v[192:195], v[60:63]
	v_mfma_f32_16x16x32_bf16 v[60:63], v[156:159], v[196:199], v[60:63]
	v_mfma_f32_16x16x32_bf16 v[64:67], v[160:163], v[192:195], v[64:67]
	v_mfma_f32_16x16x32_bf16 v[64:67], v[164:167], v[196:199], v[64:67]
	s_barrier
	s_mov_b32 m0, s86
	s_mov_b64 s[8:9], s[18:19]
	ds_read_b128 v[168:171], v246 offset:57344
	ds_read_b128 v[172:175], v246 offset:58368
	ds_read_b128 v[176:179], v246 offset:59392
	ds_read_b128 v[180:183], v246 offset:60416
	ds_read_b128 v[184:187], v246 offset:61440
	ds_read_b128 v[188:191], v246 offset:62464
	ds_read_b128 v[192:195], v246 offset:63488
	ds_read_b128 v[196:199], v246 offset:64512
	s_nop 0
	global_load_lds_dwordx4 v248, s[8:9]
	s_mov_b32 m0, s87
	s_nop 0
	global_load_lds_dwordx4 v247, s[8:9]
	s_add_u32 s8, s18, s42
	s_addc_u32 s9, s19, s43
	s_mov_b32 m0, s28
	s_nop 0
	global_load_lds_dwordx4 v248, s[8:9]
	s_mov_b32 m0, s29
	s_nop 0
	global_load_lds_dwordx4 v247, s[8:9]
	s_waitcnt vmcnt(6)
	s_waitcnt lgkmcnt(0)
	s_barrier
	s_waitcnt lgkmcnt(0)
	v_mfma_f32_16x16x32_bf16 v[68:71], v[136:139], v[168:171], v[68:71]
	v_mfma_f32_16x16x32_bf16 v[68:71], v[140:143], v[172:175], v[68:71]
	v_mfma_f32_16x16x32_bf16 v[72:75], v[144:147], v[168:171], v[72:75]
	v_mfma_f32_16x16x32_bf16 v[72:75], v[148:151], v[172:175], v[72:75]
	v_mfma_f32_16x16x32_bf16 v[76:79], v[136:139], v[176:179], v[76:79]
	v_mfma_f32_16x16x32_bf16 v[76:79], v[140:143], v[180:183], v[76:79]
	v_mfma_f32_16x16x32_bf16 v[80:83], v[144:147], v[176:179], v[80:83]
	v_mfma_f32_16x16x32_bf16 v[80:83], v[148:151], v[180:183], v[80:83]
	v_mfma_f32_16x16x32_bf16 v[84:87], v[136:139], v[184:187], v[84:87]
	v_mfma_f32_16x16x32_bf16 v[84:87], v[140:143], v[188:191], v[84:87]
	v_mfma_f32_16x16x32_bf16 v[88:91], v[144:147], v[184:187], v[88:91]
	v_mfma_f32_16x16x32_bf16 v[88:91], v[148:151], v[188:191], v[88:91]
	v_mfma_f32_16x16x32_bf16 v[92:95], v[136:139], v[192:195], v[92:95]
	v_mfma_f32_16x16x32_bf16 v[92:95], v[140:143], v[196:199], v[92:95]
	v_mfma_f32_16x16x32_bf16 v[96:99], v[144:147], v[192:195], v[96:99]
	v_mfma_f32_16x16x32_bf16 v[96:99], v[148:151], v[196:199], v[96:99]
	v_mfma_f32_16x16x32_bf16 v[100:103], v[152:155], v[168:171], v[100:103]
	v_mfma_f32_16x16x32_bf16 v[100:103], v[156:159], v[172:175], v[100:103]
	v_mfma_f32_16x16x32_bf16 v[104:107], v[160:163], v[168:171], v[104:107]
	v_mfma_f32_16x16x32_bf16 v[104:107], v[164:167], v[172:175], v[104:107]
	v_mfma_f32_16x16x32_bf16 v[108:111], v[152:155], v[176:179], v[108:111]
	v_mfma_f32_16x16x32_bf16 v[108:111], v[156:159], v[180:183], v[108:111]
	v_mfma_f32_16x16x32_bf16 v[112:115], v[160:163], v[176:179], v[112:115]
	v_mfma_f32_16x16x32_bf16 v[112:115], v[164:167], v[180:183], v[112:115]
	v_mfma_f32_16x16x32_bf16 v[116:119], v[152:155], v[184:187], v[116:119]
	v_mfma_f32_16x16x32_bf16 v[116:119], v[156:159], v[188:191], v[116:119]
	v_mfma_f32_16x16x32_bf16 v[120:123], v[160:163], v[184:187], v[120:123]
	v_mfma_f32_16x16x32_bf16 v[120:123], v[164:167], v[188:191], v[120:123]
	v_mfma_f32_16x16x32_bf16 v[124:127], v[152:155], v[192:195], v[124:127]
	v_mfma_f32_16x16x32_bf16 v[124:127], v[156:159], v[196:199], v[124:127]
	v_mfma_f32_16x16x32_bf16 v[128:131], v[160:163], v[192:195], v[128:131]
	v_mfma_f32_16x16x32_bf16 v[128:131], v[164:167], v[196:199], v[128:131]
	s_barrier
	s_add_i32 s8, s90, 2
	s_add_u32 s88, s88, 0x100
	s_addc_u32 s89, s89, 0
	s_add_u32 s26, s26, 0x100
	s_addc_u32 s27, s27, 0
	s_cmp_ge_i32 s90, s4
	s_mov_b32 s90, s8
	s_cbranch_scc0 .LBB0_855
	v_readlane_b32 s90, v255, 45
	v_readlane_b32 s91, v255, 46
	s_movk_i32 s89, 0x61

.LBB0_880:
	ds_read_b128 v[136:139], v132
	ds_read_b128 v[140:143], v132 offset:1024
	ds_read_b128 v[144:147], v132 offset:2048
	ds_read_b128 v[148:151], v132 offset:3072
	ds_read_b128 v[152:155], v133
	ds_read_b128 v[156:159], v133 offset:1024
	ds_read_b128 v[160:163], v133 offset:2048
	ds_read_b128 v[164:167], v133 offset:3072
	s_cmp_eq_u32 s4, s88
	s_cselect_b32 s17, s43, s87
	s_cselect_b32 s16, s42, s86
	s_cselect_b32 s21, s41, s27
	s_cselect_b32 s20, s40, s26
	s_add_u32 s8, s26, 0xffffff80
	s_addc_u32 s9, s27, -1
	s_mov_b32 m0, s78
	s_mov_b64 s[18:19], s[8:9]
	ds_read_b128 v[168:171], v246
	ds_read_b128 v[172:175], v246 offset:1024
	ds_read_b128 v[176:179], v246 offset:2048
	ds_read_b128 v[180:183], v246 offset:3072
	ds_read_b128 v[184:187], v246 offset:4096
	ds_read_b128 v[188:191], v246 offset:5120
	ds_read_b128 v[192:195], v246 offset:6144
	ds_read_b128 v[196:199], v246 offset:7168
	s_add_u32 s8, s8, s46
	global_load_lds_dwordx4 v242, s[18:19]
	s_mov_b32 m0, s79
	s_addc_u32 s9, s9, s47
	global_load_lds_dwordx4 v2, s[18:19]
	s_mov_b32 m0, s80
	s_add_u32 s18, s16, 0x80
	global_load_lds_dwordx4 v242, s[8:9]
	s_mov_b32 m0, s81
	s_addc_u32 s19, s17, 0
	global_load_lds_dwordx4 v2, s[8:9]
	s_waitcnt vmcnt(8)
	s_waitcnt lgkmcnt(0)
	s_barrier
	s_waitcnt lgkmcnt(0)
	v_mfma_f32_16x16x32_bf16 v[4:7], v[136:139], v[168:171], v[4:7]
	v_mfma_f32_16x16x32_bf16 v[4:7], v[140:143], v[172:175], v[4:7]
	v_mfma_f32_16x16x32_bf16 v[8:11], v[144:147], v[168:171], v[8:11]
	v_mfma_f32_16x16x32_bf16 v[8:11], v[148:151], v[172:175], v[8:11]
	v_mfma_f32_16x16x32_bf16 v[12:15], v[136:139], v[176:179], v[12:15]
	v_mfma_f32_16x16x32_bf16 v[12:15], v[140:143], v[180:183], v[12:15]
	v_mfma_f32_16x16x32_bf16 v[16:19], v[144:147], v[176:179], v[16:19]
	v_mfma_f32_16x16x32_bf16 v[16:19], v[148:151], v[180:183], v[16:19]
	v_mfma_f32_16x16x32_bf16 v[20:23], v[136:139], v[184:187], v[20:23]
	v_mfma_f32_16x16x32_bf16 v[20:23], v[140:143], v[188:191], v[20:23]
	v_mfma_f32_16x16x32_bf16 v[24:27], v[144:147], v[184:187], v[24:27]
	v_mfma_f32_16x16x32_bf16 v[24:27], v[148:151], v[188:191], v[24:27]
	v_mfma_f32_16x16x32_bf16 v[28:31], v[136:139], v[192:195], v[28:31]
	v_mfma_f32_16x16x32_bf16 v[28:31], v[140:143], v[196:199], v[28:31]
	v_mfma_f32_16x16x32_bf16 v[32:35], v[144:147], v[192:195], v[32:35]
	v_mfma_f32_16x16x32_bf16 v[32:35], v[148:151], v[196:199], v[32:35]
	v_mfma_f32_16x16x32_bf16 v[36:39], v[152:155], v[168:171], v[36:39]
	v_mfma_f32_16x16x32_bf16 v[36:39], v[156:159], v[172:175], v[36:39]
	v_mfma_f32_16x16x32_bf16 v[40:43], v[160:163], v[168:171], v[40:43]
	v_mfma_f32_16x16x32_bf16 v[40:43], v[164:167], v[172:175], v[40:43]
	v_mfma_f32_16x16x32_bf16 v[44:47], v[152:155], v[176:179], v[44:47]
	v_mfma_f32_16x16x32_bf16 v[44:47], v[156:159], v[180:183], v[44:47]
	v_mfma_f32_16x16x32_bf16 v[48:51], v[160:163], v[176:179], v[48:51]
	v_mfma_f32_16x16x32_bf16 v[48:51], v[164:167], v[180:183], v[48:51]
	v_mfma_f32_16x16x32_bf16 v[52:55], v[152:155], v[184:187], v[52:55]
	v_mfma_f32_16x16x32_bf16 v[52:55], v[156:159], v[188:191], v[52:55]
	v_mfma_f32_16x16x32_bf16 v[56:59], v[160:163], v[184:187], v[56:59]
	v_mfma_f32_16x16x32_bf16 v[56:59], v[164:167], v[188:191], v[56:59]
	v_mfma_f32_16x16x32_bf16 v[60:63], v[152:155], v[192:195], v[60:63]
	v_mfma_f32_16x16x32_bf16 v[60:63], v[156:159], v[196:199], v[60:63]
	v_mfma_f32_16x16x32_bf16 v[64:67], v[160:163], v[192:195], v[64:67]
	v_mfma_f32_16x16x32_bf16 v[64:67], v[164:167], v[196:199], v[64:67]
	s_barrier
	s_mov_b32 m0, s82
	s_mov_b64 s[8:9], s[16:17]
	ds_read_b128 v[168:171], v246 offset:16384
	ds_read_b128 v[172:175], v246 offset:17408
	ds_read_b128 v[176:179], v246 offset:18432
	ds_read_b128 v[180:183], v246 offset:19456
	ds_read_b128 v[184:187], v246 offset:20480
	ds_read_b128 v[188:191], v246 offset:21504
	ds_read_b128 v[192:195], v246 offset:22528
	ds_read_b128 v[196:199], v246 offset:23552
	s_nop 0
	global_load_lds_dwordx4 v248, s[8:9]
	s_mov_b32 m0, s83
	s_nop 0
	global_load_lds_dwordx4 v247, s[8:9]
	s_add_u32 s8, s16, s46
	s_addc_u32 s9, s17, s47
	s_mov_b32 m0, s30
	s_nop 0
	global_load_lds_dwordx4 v248, s[8:9]
	s_mov_b32 m0, s31
	s_nop 0
	global_load_lds_dwordx4 v247, s[8:9]
	s_waitcnt vmcnt(6)
	s_waitcnt lgkmcnt(0)
	s_barrier
	s_waitcnt lgkmcnt(0)
	v_mfma_f32_16x16x32_bf16 v[68:71], v[136:139], v[168:171], v[68:71]
	v_mfma_f32_16x16x32_bf16 v[68:71], v[140:143], v[172:175], v[68:71]
	v_mfma_f32_16x16x32_bf16 v[72:75], v[144:147], v[168:171], v[72:75]
	v_mfma_f32_16x16x32_bf16 v[72:75], v[148:151], v[172:175], v[72:75]
	v_mfma_f32_16x16x32_bf16 v[76:79], v[136:139], v[176:179], v[76:79]
	v_mfma_f32_16x16x32_bf16 v[76:79], v[140:143], v[180:183], v[76:79]
	v_mfma_f32_16x16x32_bf16 v[80:83], v[144:147], v[176:179], v[80:83]
	v_mfma_f32_16x16x32_bf16 v[80:83], v[148:151], v[180:183], v[80:83]
	v_mfma_f32_16x16x32_bf16 v[84:87], v[136:139], v[184:187], v[84:87]
	v_mfma_f32_16x16x32_bf16 v[84:87], v[140:143], v[188:191], v[84:87]
	v_mfma_f32_16x16x32_bf16 v[88:91], v[144:147], v[184:187], v[88:91]
	v_mfma_f32_16x16x32_bf16 v[88:91], v[148:151], v[188:191], v[88:91]
	v_mfma_f32_16x16x32_bf16 v[92:95], v[136:139], v[192:195], v[92:95]
	v_mfma_f32_16x16x32_bf16 v[92:95], v[140:143], v[196:199], v[92:95]
	v_mfma_f32_16x16x32_bf16 v[96:99], v[144:147], v[192:195], v[96:99]
	v_mfma_f32_16x16x32_bf16 v[96:99], v[148:151], v[196:199], v[96:99]
	v_mfma_f32_16x16x32_bf16 v[100:103], v[152:155], v[168:171], v[100:103]
	v_mfma_f32_16x16x32_bf16 v[100:103], v[156:159], v[172:175], v[100:103]
	v_mfma_f32_16x16x32_bf16 v[104:107], v[160:163], v[168:171], v[104:107]
	v_mfma_f32_16x16x32_bf16 v[104:107], v[164:167], v[172:175], v[104:107]
	v_mfma_f32_16x16x32_bf16 v[108:111], v[152:155], v[176:179], v[108:111]
	v_mfma_f32_16x16x32_bf16 v[108:111], v[156:159], v[180:183], v[108:111]
	v_mfma_f32_16x16x32_bf16 v[112:115], v[160:163], v[176:179], v[112:115]
	v_mfma_f32_16x16x32_bf16 v[112:115], v[164:167], v[180:183], v[112:115]
	v_mfma_f32_16x16x32_bf16 v[116:119], v[152:155], v[184:187], v[116:119]
	v_mfma_f32_16x16x32_bf16 v[116:119], v[156:159], v[188:191], v[116:119]
	v_mfma_f32_16x16x32_bf16 v[120:123], v[160:163], v[184:187], v[120:123]
	v_mfma_f32_16x16x32_bf16 v[120:123], v[164:167], v[188:191], v[120:123]
	v_mfma_f32_16x16x32_bf16 v[124:127], v[152:155], v[192:195], v[124:127]
	v_mfma_f32_16x16x32_bf16 v[124:127], v[156:159], v[196:199], v[124:127]
	v_mfma_f32_16x16x32_bf16 v[128:131], v[160:163], v[192:195], v[128:131]
	v_mfma_f32_16x16x32_bf16 v[128:131], v[164:167], v[196:199], v[128:131]
	s_barrier
	ds_read_b128 v[136:139], v134
	ds_read_b128 v[140:143], v134 offset:1024
	ds_read_b128 v[144:147], v134 offset:2048
	ds_read_b128 v[148:151], v134 offset:3072
	ds_read_b128 v[152:155], v135
	ds_read_b128 v[156:159], v135 offset:1024
	ds_read_b128 v[160:163], v135 offset:2048
	ds_read_b128 v[164:167], v135 offset:3072
	s_mov_b32 m0, s7
	s_mov_b64 s[8:9], s[20:21]
	ds_read_b128 v[168:171], v246 offset:32768
	ds_read_b128 v[172:175], v246 offset:33792
	ds_read_b128 v[176:179], v246 offset:34816
	ds_read_b128 v[180:183], v246 offset:35840
	ds_read_b128 v[184:187], v246 offset:36864
	ds_read_b128 v[188:191], v246 offset:37888
	ds_read_b128 v[192:195], v246 offset:38912
	ds_read_b128 v[196:199], v246 offset:39936
	s_nop 0
	global_load_lds_dwordx4 v242, s[8:9]
	s_mov_b32 m0, s58
	s_nop 0
	global_load_lds_dwordx4 v2, s[8:9]
	s_add_u32 s8, s20, s46
	s_addc_u32 s9, s21, s47
	s_mov_b32 m0, s59
	s_nop 0
	global_load_lds_dwordx4 v242, s[8:9]
	s_mov_b32 m0, s69
	s_nop 0
	global_load_lds_dwordx4 v2, s[8:9]
	s_waitcnt vmcnt(8)
	s_waitcnt lgkmcnt(0)
	s_barrier
	s_waitcnt lgkmcnt(0)
	v_mfma_f32_16x16x32_bf16 v[4:7], v[136:139], v[168:171], v[4:7]
	v_mfma_f32_16x16x32_bf16 v[4:7], v[140:143], v[172:175], v[4:7]
	v_mfma_f32_16x16x32_bf16 v[8:11], v[144:147], v[168:171], v[8:11]
	v_mfma_f32_16x16x32_bf16 v[8:11], v[148:151], v[172:175], v[8:11]
	v_mfma_f32_16x16x32_bf16 v[12:15], v[136:139], v[176:179], v[12:15]
	v_mfma_f32_16x16x32_bf16 v[12:15], v[140:143], v[180:183], v[12:15]
	v_mfma_f32_16x16x32_bf16 v[16:19], v[144:147], v[176:179], v[16:19]
	v_mfma_f32_16x16x32_bf16 v[16:19], v[148:151], v[180:183], v[16:19]
	v_mfma_f32_16x16x32_bf16 v[20:23], v[136:139], v[184:187], v[20:23]
	v_mfma_f32_16x16x32_bf16 v[20:23], v[140:143], v[188:191], v[20:23]
	v_mfma_f32_16x16x32_bf16 v[24:27], v[144:147], v[184:187], v[24:27]
	v_mfma_f32_16x16x32_bf16 v[24:27], v[148:151], v[188:191], v[24:27]
	v_mfma_f32_16x16x32_bf16 v[28:31], v[136:139], v[192:195], v[28:31]
	v_mfma_f32_16x16x32_bf16 v[28:31], v[140:143], v[196:199], v[28:31]
	v_mfma_f32_16x16x32_bf16 v[32:35], v[144:147], v[192:195], v[32:35]
	v_mfma_f32_16x16x32_bf16 v[32:35], v[148:151], v[196:199], v[32:35]
	v_mfma_f32_16x16x32_bf16 v[36:39], v[152:155], v[168:171], v[36:39]
	v_mfma_f32_16x16x32_bf16 v[36:39], v[156:159], v[172:175], v[36:39]
	v_mfma_f32_16x16x32_bf16 v[40:43], v[160:163], v[168:171], v[40:43]
	v_mfma_f32_16x16x32_bf16 v[40:43], v[164:167], v[172:175], v[40:43]
	v_mfma_f32_16x16x32_bf16 v[44:47], v[152:155], v[176:179], v[44:47]
	v_mfma_f32_16x16x32_bf16 v[44:47], v[156:159], v[180:183], v[44:47]
	v_mfma_f32_16x16x32_bf16 v[48:51], v[160:163], v[176:179], v[48:51]
	v_mfma_f32_16x16x32_bf16 v[48:51], v[164:167], v[180:183], v[48:51]
	v_mfma_f32_16x16x32_bf16 v[52:55], v[152:155], v[184:187], v[52:55]
	v_mfma_f32_16x16x32_bf16 v[52:55], v[156:159], v[188:191], v[52:55]
	v_mfma_f32_16x16x32_bf16 v[56:59], v[160:163], v[184:187], v[56:59]
	v_mfma_f32_16x16x32_bf16 v[56:59], v[164:167], v[188:191], v[56:59]
	v_mfma_f32_16x16x32_bf16 v[60:63], v[152:155], v[192:195], v[60:63]
	v_mfma_f32_16x16x32_bf16 v[60:63], v[156:159], v[196:199], v[60:63]
	v_mfma_f32_16x16x32_bf16 v[64:67], v[160:163], v[192:195], v[64:67]
	v_mfma_f32_16x16x32_bf16 v[64:67], v[164:167], v[196:199], v[64:67]
	s_barrier
	s_mov_b32 m0, s84
	s_mov_b64 s[8:9], s[18:19]
	ds_read_b128 v[168:171], v246 offset:49152
	ds_read_b128 v[172:175], v246 offset:50176
	ds_read_b128 v[176:179], v246 offset:51200
	ds_read_b128 v[180:183], v246 offset:52224
	ds_read_b128 v[184:187], v246 offset:53248
	ds_read_b128 v[188:191], v246 offset:54272
	ds_read_b128 v[192:195], v246 offset:55296
	ds_read_b128 v[196:199], v246 offset:56320
	s_nop 0
	global_load_lds_dwordx4 v248, s[8:9]
	s_mov_b32 m0, s85
	s_nop 0
	global_load_lds_dwordx4 v247, s[8:9]
	s_add_u32 s8, s18, s46
	s_addc_u32 s9, s19, s47
	s_mov_b32 m0, s28
	s_nop 0
	global_load_lds_dwordx4 v248, s[8:9]
	s_mov_b32 m0, s29
	s_nop 0
	global_load_lds_dwordx4 v247, s[8:9]
	s_waitcnt vmcnt(6)
	s_waitcnt lgkmcnt(0)
	s_barrier
	s_waitcnt lgkmcnt(0)
	v_mfma_f32_16x16x32_bf16 v[68:71], v[136:139], v[168:171], v[68:71]
	v_mfma_f32_16x16x32_bf16 v[68:71], v[140:143], v[172:175], v[68:71]
	v_mfma_f32_16x16x32_bf16 v[72:75], v[144:147], v[168:171], v[72:75]
	v_mfma_f32_16x16x32_bf16 v[72:75], v[148:151], v[172:175], v[72:75]
	v_mfma_f32_16x16x32_bf16 v[76:79], v[136:139], v[176:179], v[76:79]
	v_mfma_f32_16x16x32_bf16 v[76:79], v[140:143], v[180:183], v[76:79]
	v_mfma_f32_16x16x32_bf16 v[80:83], v[144:147], v[176:179], v[80:83]
	v_mfma_f32_16x16x32_bf16 v[80:83], v[148:151], v[180:183], v[80:83]
	v_mfma_f32_16x16x32_bf16 v[84:87], v[136:139], v[184:187], v[84:87]
	v_mfma_f32_16x16x32_bf16 v[84:87], v[140:143], v[188:191], v[84:87]
	v_mfma_f32_16x16x32_bf16 v[88:91], v[144:147], v[184:187], v[88:91]
	v_mfma_f32_16x16x32_bf16 v[88:91], v[148:151], v[188:191], v[88:91]
	v_mfma_f32_16x16x32_bf16 v[92:95], v[136:139], v[192:195], v[92:95]
	v_mfma_f32_16x16x32_bf16 v[92:95], v[140:143], v[196:199], v[92:95]
	v_mfma_f32_16x16x32_bf16 v[96:99], v[144:147], v[192:195], v[96:99]
	v_mfma_f32_16x16x32_bf16 v[96:99], v[148:151], v[196:199], v[96:99]
	v_mfma_f32_16x16x32_bf16 v[100:103], v[152:155], v[168:171], v[100:103]
	v_mfma_f32_16x16x32_bf16 v[100:103], v[156:159], v[172:175], v[100:103]
	v_mfma_f32_16x16x32_bf16 v[104:107], v[160:163], v[168:171], v[104:107]
	v_mfma_f32_16x16x32_bf16 v[104:107], v[164:167], v[172:175], v[104:107]
	v_mfma_f32_16x16x32_bf16 v[108:111], v[152:155], v[176:179], v[108:111]
	v_mfma_f32_16x16x32_bf16 v[108:111], v[156:159], v[180:183], v[108:111]
	v_mfma_f32_16x16x32_bf16 v[112:115], v[160:163], v[176:179], v[112:115]
	v_mfma_f32_16x16x32_bf16 v[112:115], v[164:167], v[180:183], v[112:115]
	v_mfma_f32_16x16x32_bf16 v[116:119], v[152:155], v[184:187], v[116:119]
	v_mfma_f32_16x16x32_bf16 v[116:119], v[156:159], v[188:191], v[116:119]
	v_mfma_f32_16x16x32_bf16 v[120:123], v[160:163], v[184:187], v[120:123]
	v_mfma_f32_16x16x32_bf16 v[120:123], v[164:167], v[188:191], v[120:123]
	v_mfma_f32_16x16x32_bf16 v[124:127], v[152:155], v[192:195], v[124:127]
	v_mfma_f32_16x16x32_bf16 v[124:127], v[156:159], v[196:199], v[124:127]
	v_mfma_f32_16x16x32_bf16 v[128:131], v[160:163], v[192:195], v[128:131]
	v_mfma_f32_16x16x32_bf16 v[128:131], v[164:167], v[196:199], v[128:131]
	s_barrier
	s_add_i32 s8, s88, 2
	s_add_u32 s86, s86, 0x100
	s_addc_u32 s87, s87, 0
	s_add_u32 s26, s26, 0x100
	s_addc_u32 s27, s27, 0
	s_cmp_ge_i32 s88, s4
	s_mov_b32 s88, s8
	s_cbranch_scc0 .LBB0_880

.LBB0_1021:
	ds_read_b128 v[144:147], v132
	ds_read_b128 v[148:151], v132 offset:1024
	ds_read_b128 v[152:155], v132 offset:2048
	ds_read_b128 v[156:159], v132 offset:3072
	ds_read_b128 v[160:163], v133
	ds_read_b128 v[164:167], v133 offset:1024
	ds_read_b128 v[168:171], v133 offset:2048
	ds_read_b128 v[172:175], v133 offset:3072
	s_cmp_eq_u32 s76, s97
	s_cselect_b32 s17, s43, s96
	s_cselect_b32 s16, s42, s95
	s_cselect_b32 s67, s65, s73
	s_cselect_b32 s66, s64, s72
	s_add_u32 s8, s72, 0xffffff80
	s_addc_u32 s9, s73, -1
	s_mov_b32 m0, s85
	s_mov_b64 s[18:19], s[8:9]
	ds_read_b128 v[176:179], v141 offset:8192
	ds_read_b128 v[180:183], v141 offset:9216
	ds_read_b128 v[184:187], v141 offset:10240
	ds_read_b128 v[188:191], v141 offset:11264
	ds_read_b128 v[192:195], v141 offset:12288
	ds_read_b128 v[196:199], v141 offset:13312
	ds_read_b128 v[200:203], v141 offset:14336
	ds_read_b128 v[204:207], v141 offset:15360
	s_add_u32 s8, s8, s20
	global_load_lds_dwordx4 v137, s[18:19]
	s_mov_b32 m0, s86
	s_addc_u32 s9, s9, s21
	global_load_lds_dwordx4 v136, s[18:19]
	s_mov_b32 m0, s87
	s_add_u32 s18, s16, 0x80
	global_load_lds_dwordx4 v137, s[8:9]
	s_mov_b32 m0, s88
	s_addc_u32 s19, s17, 0
	global_load_lds_dwordx4 v136, s[8:9]
	s_waitcnt vmcnt(8)
	s_waitcnt lgkmcnt(0)
	s_barrier
	s_waitcnt lgkmcnt(0)
	v_mfma_f32_16x16x32_bf16 v[4:7], v[144:147], v[176:179], v[4:7]
	v_mfma_f32_16x16x32_bf16 v[4:7], v[148:151], v[180:183], v[4:7]
	v_mfma_f32_16x16x32_bf16 v[8:11], v[152:155], v[176:179], v[8:11]
	v_mfma_f32_16x16x32_bf16 v[8:11], v[156:159], v[180:183], v[8:11]
	v_mfma_f32_16x16x32_bf16 v[12:15], v[144:147], v[184:187], v[12:15]
	v_mfma_f32_16x16x32_bf16 v[12:15], v[148:151], v[188:191], v[12:15]
	v_mfma_f32_16x16x32_bf16 v[16:19], v[152:155], v[184:187], v[16:19]
	v_mfma_f32_16x16x32_bf16 v[16:19], v[156:159], v[188:191], v[16:19]
	v_mfma_f32_16x16x32_bf16 v[20:23], v[144:147], v[192:195], v[20:23]
	v_mfma_f32_16x16x32_bf16 v[20:23], v[148:151], v[196:199], v[20:23]
	v_mfma_f32_16x16x32_bf16 v[24:27], v[152:155], v[192:195], v[24:27]
	v_mfma_f32_16x16x32_bf16 v[24:27], v[156:159], v[196:199], v[24:27]
	v_mfma_f32_16x16x32_bf16 v[28:31], v[144:147], v[200:203], v[28:31]
	v_mfma_f32_16x16x32_bf16 v[28:31], v[148:151], v[204:207], v[28:31]
	v_mfma_f32_16x16x32_bf16 v[32:35], v[152:155], v[200:203], v[32:35]
	v_mfma_f32_16x16x32_bf16 v[32:35], v[156:159], v[204:207], v[32:35]
	v_mfma_f32_16x16x32_bf16 v[36:39], v[160:163], v[176:179], v[36:39]
	v_mfma_f32_16x16x32_bf16 v[36:39], v[164:167], v[180:183], v[36:39]
	v_mfma_f32_16x16x32_bf16 v[40:43], v[168:171], v[176:179], v[40:43]
	v_mfma_f32_16x16x32_bf16 v[40:43], v[172:175], v[180:183], v[40:43]
	v_mfma_f32_16x16x32_bf16 v[44:47], v[160:163], v[184:187], v[44:47]
	v_mfma_f32_16x16x32_bf16 v[44:47], v[164:167], v[188:191], v[44:47]
	v_mfma_f32_16x16x32_bf16 v[48:51], v[168:171], v[184:187], v[48:51]
	v_mfma_f32_16x16x32_bf16 v[48:51], v[172:175], v[188:191], v[48:51]
	v_mfma_f32_16x16x32_bf16 v[52:55], v[160:163], v[192:195], v[52:55]
	v_mfma_f32_16x16x32_bf16 v[52:55], v[164:167], v[196:199], v[52:55]
	v_mfma_f32_16x16x32_bf16 v[56:59], v[168:171], v[192:195], v[56:59]
	v_mfma_f32_16x16x32_bf16 v[56:59], v[172:175], v[196:199], v[56:59]
	v_mfma_f32_16x16x32_bf16 v[60:63], v[160:163], v[200:203], v[60:63]
	v_mfma_f32_16x16x32_bf16 v[60:63], v[164:167], v[204:207], v[60:63]
	v_mfma_f32_16x16x32_bf16 v[64:67], v[168:171], v[200:203], v[64:67]
	v_mfma_f32_16x16x32_bf16 v[64:67], v[172:175], v[204:207], v[64:67]
	s_barrier
	s_mov_b32 m0, s89
	s_mov_b64 s[8:9], s[16:17]
	ds_read_b128 v[176:179], v141 offset:24576
	ds_read_b128 v[180:183], v141 offset:25600
	ds_read_b128 v[184:187], v141 offset:26624
	ds_read_b128 v[188:191], v141 offset:27648
	ds_read_b128 v[192:195], v141 offset:28672
	ds_read_b128 v[196:199], v141 offset:29696
	ds_read_b128 v[200:203], v141 offset:30720
	ds_read_b128 v[204:207], v141 offset:31744
	s_nop 0
	global_load_lds_dwordx4 v143, s[8:9]
	s_mov_b32 m0, s90
	s_nop 0
	global_load_lds_dwordx4 v142, s[8:9]
	s_add_u32 s8, s16, s20
	s_addc_u32 s9, s17, s21
	s_mov_b32 m0, s91
	s_nop 0
	global_load_lds_dwordx4 v143, s[8:9]
	s_mov_b32 m0, s92
	s_nop 0
	global_load_lds_dwordx4 v142, s[8:9]
	s_waitcnt vmcnt(6)
	s_waitcnt lgkmcnt(0)
	s_barrier
	s_waitcnt lgkmcnt(0)
	v_mfma_f32_16x16x32_bf16 v[68:71], v[144:147], v[176:179], v[68:71]
	v_mfma_f32_16x16x32_bf16 v[68:71], v[148:151], v[180:183], v[68:71]
	v_mfma_f32_16x16x32_bf16 v[72:75], v[152:155], v[176:179], v[72:75]
	v_mfma_f32_16x16x32_bf16 v[72:75], v[156:159], v[180:183], v[72:75]
	v_mfma_f32_16x16x32_bf16 v[76:79], v[144:147], v[184:187], v[76:79]
	v_mfma_f32_16x16x32_bf16 v[76:79], v[148:151], v[188:191], v[76:79]
	v_mfma_f32_16x16x32_bf16 v[80:83], v[152:155], v[184:187], v[80:83]
	v_mfma_f32_16x16x32_bf16 v[80:83], v[156:159], v[188:191], v[80:83]
	v_mfma_f32_16x16x32_bf16 v[84:87], v[144:147], v[192:195], v[84:87]
	v_mfma_f32_16x16x32_bf16 v[84:87], v[148:151], v[196:199], v[84:87]
	v_mfma_f32_16x16x32_bf16 v[88:91], v[152:155], v[192:195], v[88:91]
	v_mfma_f32_16x16x32_bf16 v[88:91], v[156:159], v[196:199], v[88:91]
	v_mfma_f32_16x16x32_bf16 v[92:95], v[144:147], v[200:203], v[92:95]
	v_mfma_f32_16x16x32_bf16 v[92:95], v[148:151], v[204:207], v[92:95]
	v_mfma_f32_16x16x32_bf16 v[96:99], v[152:155], v[200:203], v[96:99]
	v_mfma_f32_16x16x32_bf16 v[96:99], v[156:159], v[204:207], v[96:99]
	v_mfma_f32_16x16x32_bf16 v[100:103], v[160:163], v[176:179], v[100:103]
	v_mfma_f32_16x16x32_bf16 v[100:103], v[164:167], v[180:183], v[100:103]
	v_mfma_f32_16x16x32_bf16 v[104:107], v[168:171], v[176:179], v[104:107]
	v_mfma_f32_16x16x32_bf16 v[104:107], v[172:175], v[180:183], v[104:107]
	v_mfma_f32_16x16x32_bf16 v[108:111], v[160:163], v[184:187], v[108:111]
	v_mfma_f32_16x16x32_bf16 v[108:111], v[164:167], v[188:191], v[108:111]
	v_mfma_f32_16x16x32_bf16 v[112:115], v[168:171], v[184:187], v[112:115]
	v_mfma_f32_16x16x32_bf16 v[112:115], v[172:175], v[188:191], v[112:115]
	v_mfma_f32_16x16x32_bf16 v[116:119], v[160:163], v[192:195], v[116:119]
	v_mfma_f32_16x16x32_bf16 v[116:119], v[164:167], v[196:199], v[116:119]
	v_mfma_f32_16x16x32_bf16 v[120:123], v[168:171], v[192:195], v[120:123]
	v_mfma_f32_16x16x32_bf16 v[120:123], v[172:175], v[196:199], v[120:123]
	v_mfma_f32_16x16x32_bf16 v[124:127], v[160:163], v[200:203], v[124:127]
	v_mfma_f32_16x16x32_bf16 v[124:127], v[164:167], v[204:207], v[124:127]
	v_mfma_f32_16x16x32_bf16 v[128:131], v[168:171], v[200:203], v[128:131]
	v_mfma_f32_16x16x32_bf16 v[128:131], v[172:175], v[204:207], v[128:131]
	s_barrier
	ds_read_b128 v[144:147], v134
	ds_read_b128 v[148:151], v134 offset:1024
	ds_read_b128 v[152:155], v134 offset:2048
	ds_read_b128 v[156:159], v134 offset:3072
	ds_read_b128 v[160:163], v135
	ds_read_b128 v[164:167], v135 offset:1024
	ds_read_b128 v[168:171], v135 offset:2048
	ds_read_b128 v[172:175], v135 offset:3072
	s_mov_b32 m0, s78
	s_mov_b64 s[8:9], s[66:67]
	ds_read_b128 v[176:179], v141 offset:40960
	ds_read_b128 v[180:183], v141 offset:41984
	ds_read_b128 v[184:187], v141 offset:43008
	ds_read_b128 v[188:191], v141 offset:44032
	ds_read_b128 v[192:195], v141 offset:45056
	ds_read_b128 v[196:199], v141 offset:46080
	ds_read_b128 v[200:203], v141 offset:47104
	ds_read_b128 v[204:207], v141 offset:48128
	s_nop 0
	global_load_lds_dwordx4 v137, s[8:9]
	s_mov_b32 m0, s79
	s_nop 0
	global_load_lds_dwordx4 v136, s[8:9]
	s_add_u32 s8, s66, s20
	s_addc_u32 s9, s67, s21
	s_mov_b32 m0, s80
	s_nop 0
	global_load_lds_dwordx4 v137, s[8:9]
	s_mov_b32 m0, s81
	s_nop 0
	global_load_lds_dwordx4 v136, s[8:9]
	s_waitcnt vmcnt(8)
	s_waitcnt lgkmcnt(0)
	s_barrier
	s_waitcnt lgkmcnt(0)
	v_mfma_f32_16x16x32_bf16 v[4:7], v[144:147], v[176:179], v[4:7]
	v_mfma_f32_16x16x32_bf16 v[4:7], v[148:151], v[180:183], v[4:7]
	v_mfma_f32_16x16x32_bf16 v[8:11], v[152:155], v[176:179], v[8:11]
	v_mfma_f32_16x16x32_bf16 v[8:11], v[156:159], v[180:183], v[8:11]
	v_mfma_f32_16x16x32_bf16 v[12:15], v[144:147], v[184:187], v[12:15]
	v_mfma_f32_16x16x32_bf16 v[12:15], v[148:151], v[188:191], v[12:15]
	v_mfma_f32_16x16x32_bf16 v[16:19], v[152:155], v[184:187], v[16:19]
	v_mfma_f32_16x16x32_bf16 v[16:19], v[156:159], v[188:191], v[16:19]
	v_mfma_f32_16x16x32_bf16 v[20:23], v[144:147], v[192:195], v[20:23]
	v_mfma_f32_16x16x32_bf16 v[20:23], v[148:151], v[196:199], v[20:23]
	v_mfma_f32_16x16x32_bf16 v[24:27], v[152:155], v[192:195], v[24:27]
	v_mfma_f32_16x16x32_bf16 v[24:27], v[156:159], v[196:199], v[24:27]
	v_mfma_f32_16x16x32_bf16 v[28:31], v[144:147], v[200:203], v[28:31]
	v_mfma_f32_16x16x32_bf16 v[28:31], v[148:151], v[204:207], v[28:31]
	v_mfma_f32_16x16x32_bf16 v[32:35], v[152:155], v[200:203], v[32:35]
	v_mfma_f32_16x16x32_bf16 v[32:35], v[156:159], v[204:207], v[32:35]
	v_mfma_f32_16x16x32_bf16 v[36:39], v[160:163], v[176:179], v[36:39]
	v_mfma_f32_16x16x32_bf16 v[36:39], v[164:167], v[180:183], v[36:39]
	v_mfma_f32_16x16x32_bf16 v[40:43], v[168:171], v[176:179], v[40:43]
	v_mfma_f32_16x16x32_bf16 v[40:43], v[172:175], v[180:183], v[40:43]
	v_mfma_f32_16x16x32_bf16 v[44:47], v[160:163], v[184:187], v[44:47]
	v_mfma_f32_16x16x32_bf16 v[44:47], v[164:167], v[188:191], v[44:47]
	v_mfma_f32_16x16x32_bf16 v[48:51], v[168:171], v[184:187], v[48:51]
	v_mfma_f32_16x16x32_bf16 v[48:51], v[172:175], v[188:191], v[48:51]
	v_mfma_f32_16x16x32_bf16 v[52:55], v[160:163], v[192:195], v[52:55]
	v_mfma_f32_16x16x32_bf16 v[52:55], v[164:167], v[196:199], v[52:55]
	v_mfma_f32_16x16x32_bf16 v[56:59], v[168:171], v[192:195], v[56:59]
	v_mfma_f32_16x16x32_bf16 v[56:59], v[172:175], v[196:199], v[56:59]
	v_mfma_f32_16x16x32_bf16 v[60:63], v[160:163], v[200:203], v[60:63]
	v_mfma_f32_16x16x32_bf16 v[60:63], v[164:167], v[204:207], v[60:63]
	v_mfma_f32_16x16x32_bf16 v[64:67], v[168:171], v[200:203], v[64:67]
	v_mfma_f32_16x16x32_bf16 v[64:67], v[172:175], v[204:207], v[64:67]
	s_barrier
	s_mov_b32 m0, s68
	s_mov_b64 s[8:9], s[18:19]
	ds_read_b128 v[176:179], v141 offset:57344
	ds_read_b128 v[180:183], v141 offset:58368
	ds_read_b128 v[184:187], v141 offset:59392
	ds_read_b128 v[188:191], v141 offset:60416
	ds_read_b128 v[192:195], v141 offset:61440
	ds_read_b128 v[196:199], v141 offset:62464
	ds_read_b128 v[200:203], v141 offset:63488
	ds_read_b128 v[204:207], v141 offset:64512
	s_nop 0
	global_load_lds_dwordx4 v143, s[8:9]
	s_mov_b32 m0, s69
	s_nop 0
	global_load_lds_dwordx4 v142, s[8:9]
	s_add_u32 s8, s18, s20
	s_addc_u32 s9, s19, s21
	s_mov_b32 m0, s93
	s_nop 0
	global_load_lds_dwordx4 v143, s[8:9]
	s_mov_b32 m0, s94
	s_nop 0
	global_load_lds_dwordx4 v142, s[8:9]
	s_waitcnt vmcnt(6)
	s_waitcnt lgkmcnt(0)
	s_barrier
	s_waitcnt lgkmcnt(0)
	v_mfma_f32_16x16x32_bf16 v[68:71], v[144:147], v[176:179], v[68:71]
	v_mfma_f32_16x16x32_bf16 v[68:71], v[148:151], v[180:183], v[68:71]
	v_mfma_f32_16x16x32_bf16 v[72:75], v[152:155], v[176:179], v[72:75]
	v_mfma_f32_16x16x32_bf16 v[72:75], v[156:159], v[180:183], v[72:75]
	v_mfma_f32_16x16x32_bf16 v[76:79], v[144:147], v[184:187], v[76:79]
	v_mfma_f32_16x16x32_bf16 v[76:79], v[148:151], v[188:191], v[76:79]
	v_mfma_f32_16x16x32_bf16 v[80:83], v[152:155], v[184:187], v[80:83]
	v_mfma_f32_16x16x32_bf16 v[80:83], v[156:159], v[188:191], v[80:83]
	v_mfma_f32_16x16x32_bf16 v[84:87], v[144:147], v[192:195], v[84:87]
	v_mfma_f32_16x16x32_bf16 v[84:87], v[148:151], v[196:199], v[84:87]
	v_mfma_f32_16x16x32_bf16 v[88:91], v[152:155], v[192:195], v[88:91]
	v_mfma_f32_16x16x32_bf16 v[88:91], v[156:159], v[196:199], v[88:91]
	v_mfma_f32_16x16x32_bf16 v[92:95], v[144:147], v[200:203], v[92:95]
	v_mfma_f32_16x16x32_bf16 v[92:95], v[148:151], v[204:207], v[92:95]
	v_mfma_f32_16x16x32_bf16 v[96:99], v[152:155], v[200:203], v[96:99]
	v_mfma_f32_16x16x32_bf16 v[96:99], v[156:159], v[204:207], v[96:99]
	v_mfma_f32_16x16x32_bf16 v[100:103], v[160:163], v[176:179], v[100:103]
	v_mfma_f32_16x16x32_bf16 v[100:103], v[164:167], v[180:183], v[100:103]
	v_mfma_f32_16x16x32_bf16 v[104:107], v[168:171], v[176:179], v[104:107]
	v_mfma_f32_16x16x32_bf16 v[104:107], v[172:175], v[180:183], v[104:107]
	v_mfma_f32_16x16x32_bf16 v[108:111], v[160:163], v[184:187], v[108:111]
	v_mfma_f32_16x16x32_bf16 v[108:111], v[164:167], v[188:191], v[108:111]
	v_mfma_f32_16x16x32_bf16 v[112:115], v[168:171], v[184:187], v[112:115]
	v_mfma_f32_16x16x32_bf16 v[112:115], v[172:175], v[188:191], v[112:115]
	v_mfma_f32_16x16x32_bf16 v[116:119], v[160:163], v[192:195], v[116:119]
	v_mfma_f32_16x16x32_bf16 v[116:119], v[164:167], v[196:199], v[116:119]
	v_mfma_f32_16x16x32_bf16 v[120:123], v[168:171], v[192:195], v[120:123]
	v_mfma_f32_16x16x32_bf16 v[120:123], v[172:175], v[196:199], v[120:123]
	v_mfma_f32_16x16x32_bf16 v[124:127], v[160:163], v[200:203], v[124:127]
	v_mfma_f32_16x16x32_bf16 v[124:127], v[164:167], v[204:207], v[124:127]
	v_mfma_f32_16x16x32_bf16 v[128:131], v[168:171], v[200:203], v[128:131]
	v_mfma_f32_16x16x32_bf16 v[128:131], v[172:175], v[204:207], v[128:131]
	s_barrier
	s_add_i32 s8, s97, 2
	s_add_u32 s95, s95, 0x100
	s_addc_u32 s96, s96, 0
	s_add_u32 s72, s72, 0x100
	s_addc_u32 s73, s73, 0
	s_cmp_ge_i32 s97, s76
	s_mov_b32 s97, s8
	s_cbranch_scc0 .LBB0_1021
	v_readlane_b32 s96, v255, 41
	v_readlane_b32 s97, v255, 42

.LBB0_1042:
	ds_read_b128 v[144:147], v132
	ds_read_b128 v[148:151], v132 offset:1024
	ds_read_b128 v[152:155], v132 offset:2048
	ds_read_b128 v[156:159], v132 offset:3072
	ds_read_b128 v[160:163], v133
	ds_read_b128 v[164:167], v133 offset:1024
	ds_read_b128 v[168:171], v133 offset:2048
	ds_read_b128 v[172:175], v133 offset:3072
	s_cmp_eq_u32 s72, s95
	s_cselect_b32 s17, s43, s94
	s_cselect_b32 s16, s42, s93
	s_cselect_b32 s65, s41, s67
	s_cselect_b32 s64, s40, s66
	s_add_u32 s8, s66, 0xffffff80
	s_addc_u32 s9, s67, -1
	s_mov_b32 m0, s83
	s_mov_b64 s[18:19], s[8:9]
	ds_read_b128 v[176:179], v141
	ds_read_b128 v[180:183], v141 offset:1024
	ds_read_b128 v[184:187], v141 offset:2048
	ds_read_b128 v[188:191], v141 offset:3072
	ds_read_b128 v[192:195], v141 offset:4096
	ds_read_b128 v[196:199], v141 offset:5120
	ds_read_b128 v[200:203], v141 offset:6144
	ds_read_b128 v[204:207], v141 offset:7168
	s_add_u32 s8, s8, s20
	global_load_lds_dwordx4 v137, s[18:19]
	s_mov_b32 m0, s84
	s_addc_u32 s9, s9, s21
	global_load_lds_dwordx4 v136, s[18:19]
	s_mov_b32 m0, s85
	s_add_u32 s18, s16, 0x80
	global_load_lds_dwordx4 v137, s[8:9]
	s_mov_b32 m0, s86
	s_addc_u32 s19, s17, 0
	global_load_lds_dwordx4 v136, s[8:9]
	s_waitcnt vmcnt(8)
	s_waitcnt lgkmcnt(0)
	s_barrier
	s_waitcnt lgkmcnt(0)
	v_mfma_f32_16x16x32_bf16 v[4:7], v[144:147], v[176:179], v[4:7]
	v_mfma_f32_16x16x32_bf16 v[4:7], v[148:151], v[180:183], v[4:7]
	v_mfma_f32_16x16x32_bf16 v[8:11], v[152:155], v[176:179], v[8:11]
	v_mfma_f32_16x16x32_bf16 v[8:11], v[156:159], v[180:183], v[8:11]
	v_mfma_f32_16x16x32_bf16 v[12:15], v[144:147], v[184:187], v[12:15]
	v_mfma_f32_16x16x32_bf16 v[12:15], v[148:151], v[188:191], v[12:15]
	v_mfma_f32_16x16x32_bf16 v[16:19], v[152:155], v[184:187], v[16:19]
	v_mfma_f32_16x16x32_bf16 v[16:19], v[156:159], v[188:191], v[16:19]
	v_mfma_f32_16x16x32_bf16 v[20:23], v[144:147], v[192:195], v[20:23]
	v_mfma_f32_16x16x32_bf16 v[20:23], v[148:151], v[196:199], v[20:23]
	v_mfma_f32_16x16x32_bf16 v[24:27], v[152:155], v[192:195], v[24:27]
	v_mfma_f32_16x16x32_bf16 v[24:27], v[156:159], v[196:199], v[24:27]
	v_mfma_f32_16x16x32_bf16 v[28:31], v[144:147], v[200:203], v[28:31]
	v_mfma_f32_16x16x32_bf16 v[28:31], v[148:151], v[204:207], v[28:31]
	v_mfma_f32_16x16x32_bf16 v[32:35], v[152:155], v[200:203], v[32:35]
	v_mfma_f32_16x16x32_bf16 v[32:35], v[156:159], v[204:207], v[32:35]
	v_mfma_f32_16x16x32_bf16 v[36:39], v[160:163], v[176:179], v[36:39]
	v_mfma_f32_16x16x32_bf16 v[36:39], v[164:167], v[180:183], v[36:39]
	v_mfma_f32_16x16x32_bf16 v[40:43], v[168:171], v[176:179], v[40:43]
	v_mfma_f32_16x16x32_bf16 v[40:43], v[172:175], v[180:183], v[40:43]
	v_mfma_f32_16x16x32_bf16 v[44:47], v[160:163], v[184:187], v[44:47]
	v_mfma_f32_16x16x32_bf16 v[44:47], v[164:167], v[188:191], v[44:47]
	v_mfma_f32_16x16x32_bf16 v[48:51], v[168:171], v[184:187], v[48:51]
	v_mfma_f32_16x16x32_bf16 v[48:51], v[172:175], v[188:191], v[48:51]
	v_mfma_f32_16x16x32_bf16 v[52:55], v[160:163], v[192:195], v[52:55]
	v_mfma_f32_16x16x32_bf16 v[52:55], v[164:167], v[196:199], v[52:55]
	v_mfma_f32_16x16x32_bf16 v[56:59], v[168:171], v[192:195], v[56:59]
	v_mfma_f32_16x16x32_bf16 v[56:59], v[172:175], v[196:199], v[56:59]
	v_mfma_f32_16x16x32_bf16 v[60:63], v[160:163], v[200:203], v[60:63]
	v_mfma_f32_16x16x32_bf16 v[60:63], v[164:167], v[204:207], v[60:63]
	v_mfma_f32_16x16x32_bf16 v[64:67], v[168:171], v[200:203], v[64:67]
	v_mfma_f32_16x16x32_bf16 v[64:67], v[172:175], v[204:207], v[64:67]
	s_barrier
	s_mov_b32 m0, s87
	s_mov_b64 s[8:9], s[16:17]
	ds_read_b128 v[176:179], v141 offset:16384
	ds_read_b128 v[180:183], v141 offset:17408
	ds_read_b128 v[184:187], v141 offset:18432
	ds_read_b128 v[188:191], v141 offset:19456
	ds_read_b128 v[192:195], v141 offset:20480
	ds_read_b128 v[196:199], v141 offset:21504
	ds_read_b128 v[200:203], v141 offset:22528
	ds_read_b128 v[204:207], v141 offset:23552
	s_nop 0
	global_load_lds_dwordx4 v143, s[8:9]
	s_mov_b32 m0, s88
	s_nop 0
	global_load_lds_dwordx4 v142, s[8:9]
	s_add_u32 s8, s16, s20
	s_addc_u32 s9, s17, s21
	s_mov_b32 m0, s89
	s_nop 0
	global_load_lds_dwordx4 v143, s[8:9]
	s_mov_b32 m0, s90
	s_nop 0
	global_load_lds_dwordx4 v142, s[8:9]
	s_waitcnt vmcnt(6)
	s_waitcnt lgkmcnt(0)
	s_barrier
	s_waitcnt lgkmcnt(0)
	v_mfma_f32_16x16x32_bf16 v[68:71], v[144:147], v[176:179], v[68:71]
	v_mfma_f32_16x16x32_bf16 v[68:71], v[148:151], v[180:183], v[68:71]
	v_mfma_f32_16x16x32_bf16 v[72:75], v[152:155], v[176:179], v[72:75]
	v_mfma_f32_16x16x32_bf16 v[72:75], v[156:159], v[180:183], v[72:75]
	v_mfma_f32_16x16x32_bf16 v[76:79], v[144:147], v[184:187], v[76:79]
	v_mfma_f32_16x16x32_bf16 v[76:79], v[148:151], v[188:191], v[76:79]
	v_mfma_f32_16x16x32_bf16 v[80:83], v[152:155], v[184:187], v[80:83]
	v_mfma_f32_16x16x32_bf16 v[80:83], v[156:159], v[188:191], v[80:83]
	v_mfma_f32_16x16x32_bf16 v[84:87], v[144:147], v[192:195], v[84:87]
	v_mfma_f32_16x16x32_bf16 v[84:87], v[148:151], v[196:199], v[84:87]
	v_mfma_f32_16x16x32_bf16 v[88:91], v[152:155], v[192:195], v[88:91]
	v_mfma_f32_16x16x32_bf16 v[88:91], v[156:159], v[196:199], v[88:91]
	v_mfma_f32_16x16x32_bf16 v[92:95], v[144:147], v[200:203], v[92:95]
	v_mfma_f32_16x16x32_bf16 v[92:95], v[148:151], v[204:207], v[92:95]
	v_mfma_f32_16x16x32_bf16 v[96:99], v[152:155], v[200:203], v[96:99]
	v_mfma_f32_16x16x32_bf16 v[96:99], v[156:159], v[204:207], v[96:99]
	v_mfma_f32_16x16x32_bf16 v[100:103], v[160:163], v[176:179], v[100:103]
	v_mfma_f32_16x16x32_bf16 v[100:103], v[164:167], v[180:183], v[100:103]
	v_mfma_f32_16x16x32_bf16 v[104:107], v[168:171], v[176:179], v[104:107]
	v_mfma_f32_16x16x32_bf16 v[104:107], v[172:175], v[180:183], v[104:107]
	v_mfma_f32_16x16x32_bf16 v[108:111], v[160:163], v[184:187], v[108:111]
	v_mfma_f32_16x16x32_bf16 v[108:111], v[164:167], v[188:191], v[108:111]
	v_mfma_f32_16x16x32_bf16 v[112:115], v[168:171], v[184:187], v[112:115]
	v_mfma_f32_16x16x32_bf16 v[112:115], v[172:175], v[188:191], v[112:115]
	v_mfma_f32_16x16x32_bf16 v[116:119], v[160:163], v[192:195], v[116:119]
	v_mfma_f32_16x16x32_bf16 v[116:119], v[164:167], v[196:199], v[116:119]
	v_mfma_f32_16x16x32_bf16 v[120:123], v[168:171], v[192:195], v[120:123]
	v_mfma_f32_16x16x32_bf16 v[120:123], v[172:175], v[196:199], v[120:123]
	v_mfma_f32_16x16x32_bf16 v[124:127], v[160:163], v[200:203], v[124:127]
	v_mfma_f32_16x16x32_bf16 v[124:127], v[164:167], v[204:207], v[124:127]
	v_mfma_f32_16x16x32_bf16 v[128:131], v[168:171], v[200:203], v[128:131]
	v_mfma_f32_16x16x32_bf16 v[128:131], v[172:175], v[204:207], v[128:131]
	s_barrier
	ds_read_b128 v[144:147], v134
	ds_read_b128 v[148:151], v134 offset:1024
	ds_read_b128 v[152:155], v134 offset:2048
	ds_read_b128 v[156:159], v134 offset:3072
	ds_read_b128 v[160:163], v135
	ds_read_b128 v[164:167], v135 offset:1024
	ds_read_b128 v[168:171], v135 offset:2048
	ds_read_b128 v[172:175], v135 offset:3072
	s_mov_b32 m0, s76
	s_mov_b64 s[8:9], s[64:65]
	ds_read_b128 v[176:179], v141 offset:32768
	ds_read_b128 v[180:183], v141 offset:33792
	ds_read_b128 v[184:187], v141 offset:34816
	ds_read_b128 v[188:191], v141 offset:35840
	ds_read_b128 v[192:195], v141 offset:36864
	ds_read_b128 v[196:199], v141 offset:37888
	ds_read_b128 v[200:203], v141 offset:38912
	ds_read_b128 v[204:207], v141 offset:39936
	s_nop 0
	global_load_lds_dwordx4 v137, s[8:9]
	s_mov_b32 m0, s77
	s_nop 0
	global_load_lds_dwordx4 v136, s[8:9]
	s_add_u32 s8, s64, s20
	s_addc_u32 s9, s65, s21
	s_mov_b32 m0, s78
	s_nop 0
	global_load_lds_dwordx4 v137, s[8:9]
	s_mov_b32 m0, s79
	s_nop 0
	global_load_lds_dwordx4 v136, s[8:9]
	s_waitcnt vmcnt(8)
	s_waitcnt lgkmcnt(0)
	s_barrier
	s_waitcnt lgkmcnt(0)
	v_mfma_f32_16x16x32_bf16 v[4:7], v[144:147], v[176:179], v[4:7]
	v_mfma_f32_16x16x32_bf16 v[4:7], v[148:151], v[180:183], v[4:7]
	v_mfma_f32_16x16x32_bf16 v[8:11], v[152:155], v[176:179], v[8:11]
	v_mfma_f32_16x16x32_bf16 v[8:11], v[156:159], v[180:183], v[8:11]
	v_mfma_f32_16x16x32_bf16 v[12:15], v[144:147], v[184:187], v[12:15]
	v_mfma_f32_16x16x32_bf16 v[12:15], v[148:151], v[188:191], v[12:15]
	v_mfma_f32_16x16x32_bf16 v[16:19], v[152:155], v[184:187], v[16:19]
	v_mfma_f32_16x16x32_bf16 v[16:19], v[156:159], v[188:191], v[16:19]
	v_mfma_f32_16x16x32_bf16 v[20:23], v[144:147], v[192:195], v[20:23]
	v_mfma_f32_16x16x32_bf16 v[20:23], v[148:151], v[196:199], v[20:23]
	v_mfma_f32_16x16x32_bf16 v[24:27], v[152:155], v[192:195], v[24:27]
	v_mfma_f32_16x16x32_bf16 v[24:27], v[156:159], v[196:199], v[24:27]
	v_mfma_f32_16x16x32_bf16 v[28:31], v[144:147], v[200:203], v[28:31]
	v_mfma_f32_16x16x32_bf16 v[28:31], v[148:151], v[204:207], v[28:31]
	v_mfma_f32_16x16x32_bf16 v[32:35], v[152:155], v[200:203], v[32:35]
	v_mfma_f32_16x16x32_bf16 v[32:35], v[156:159], v[204:207], v[32:35]
	v_mfma_f32_16x16x32_bf16 v[36:39], v[160:163], v[176:179], v[36:39]
	v_mfma_f32_16x16x32_bf16 v[36:39], v[164:167], v[180:183], v[36:39]
	v_mfma_f32_16x16x32_bf16 v[40:43], v[168:171], v[176:179], v[40:43]
	v_mfma_f32_16x16x32_bf16 v[40:43], v[172:175], v[180:183], v[40:43]
	v_mfma_f32_16x16x32_bf16 v[44:47], v[160:163], v[184:187], v[44:47]
	v_mfma_f32_16x16x32_bf16 v[44:47], v[164:167], v[188:191], v[44:47]
	v_mfma_f32_16x16x32_bf16 v[48:51], v[168:171], v[184:187], v[48:51]
	v_mfma_f32_16x16x32_bf16 v[48:51], v[172:175], v[188:191], v[48:51]
	v_mfma_f32_16x16x32_bf16 v[52:55], v[160:163], v[192:195], v[52:55]
	v_mfma_f32_16x16x32_bf16 v[52:55], v[164:167], v[196:199], v[52:55]
	v_mfma_f32_16x16x32_bf16 v[56:59], v[168:171], v[192:195], v[56:59]
	v_mfma_f32_16x16x32_bf16 v[56:59], v[172:175], v[196:199], v[56:59]
	v_mfma_f32_16x16x32_bf16 v[60:63], v[160:163], v[200:203], v[60:63]
	v_mfma_f32_16x16x32_bf16 v[60:63], v[164:167], v[204:207], v[60:63]
	v_mfma_f32_16x16x32_bf16 v[64:67], v[168:171], v[200:203], v[64:67]
	v_mfma_f32_16x16x32_bf16 v[64:67], v[172:175], v[204:207], v[64:67]
	s_barrier
	s_mov_b32 m0, s68
	s_mov_b64 s[8:9], s[18:19]
	ds_read_b128 v[176:179], v141 offset:49152
	ds_read_b128 v[180:183], v141 offset:50176
	ds_read_b128 v[184:187], v141 offset:51200
	ds_read_b128 v[188:191], v141 offset:52224
	ds_read_b128 v[192:195], v141 offset:53248
	ds_read_b128 v[196:199], v141 offset:54272
	ds_read_b128 v[200:203], v141 offset:55296
	ds_read_b128 v[204:207], v141 offset:56320
	s_nop 0
	global_load_lds_dwordx4 v143, s[8:9]
	s_mov_b32 m0, s69
	s_nop 0
	global_load_lds_dwordx4 v142, s[8:9]
	s_add_u32 s8, s18, s20
	s_addc_u32 s9, s19, s21
	s_mov_b32 m0, s91
	s_nop 0
	global_load_lds_dwordx4 v143, s[8:9]
	s_mov_b32 m0, s92
	s_nop 0
	global_load_lds_dwordx4 v142, s[8:9]
	s_waitcnt vmcnt(6)
	s_waitcnt lgkmcnt(0)
	s_barrier
	s_waitcnt lgkmcnt(0)
	v_mfma_f32_16x16x32_bf16 v[68:71], v[144:147], v[176:179], v[68:71]
	v_mfma_f32_16x16x32_bf16 v[68:71], v[148:151], v[180:183], v[68:71]
	v_mfma_f32_16x16x32_bf16 v[72:75], v[152:155], v[176:179], v[72:75]
	v_mfma_f32_16x16x32_bf16 v[72:75], v[156:159], v[180:183], v[72:75]
	v_mfma_f32_16x16x32_bf16 v[76:79], v[144:147], v[184:187], v[76:79]
	v_mfma_f32_16x16x32_bf16 v[76:79], v[148:151], v[188:191], v[76:79]
	v_mfma_f32_16x16x32_bf16 v[80:83], v[152:155], v[184:187], v[80:83]
	v_mfma_f32_16x16x32_bf16 v[80:83], v[156:159], v[188:191], v[80:83]
	v_mfma_f32_16x16x32_bf16 v[84:87], v[144:147], v[192:195], v[84:87]
	v_mfma_f32_16x16x32_bf16 v[84:87], v[148:151], v[196:199], v[84:87]
	v_mfma_f32_16x16x32_bf16 v[88:91], v[152:155], v[192:195], v[88:91]
	v_mfma_f32_16x16x32_bf16 v[88:91], v[156:159], v[196:199], v[88:91]
	v_mfma_f32_16x16x32_bf16 v[92:95], v[144:147], v[200:203], v[92:95]
	v_mfma_f32_16x16x32_bf16 v[92:95], v[148:151], v[204:207], v[92:95]
	v_mfma_f32_16x16x32_bf16 v[96:99], v[152:155], v[200:203], v[96:99]
	v_mfma_f32_16x16x32_bf16 v[96:99], v[156:159], v[204:207], v[96:99]
	v_mfma_f32_16x16x32_bf16 v[100:103], v[160:163], v[176:179], v[100:103]
	v_mfma_f32_16x16x32_bf16 v[100:103], v[164:167], v[180:183], v[100:103]
	v_mfma_f32_16x16x32_bf16 v[104:107], v[168:171], v[176:179], v[104:107]
	v_mfma_f32_16x16x32_bf16 v[104:107], v[172:175], v[180:183], v[104:107]
	v_mfma_f32_16x16x32_bf16 v[108:111], v[160:163], v[184:187], v[108:111]
	v_mfma_f32_16x16x32_bf16 v[108:111], v[164:167], v[188:191], v[108:111]
	v_mfma_f32_16x16x32_bf16 v[112:115], v[168:171], v[184:187], v[112:115]
	v_mfma_f32_16x16x32_bf16 v[112:115], v[172:175], v[188:191], v[112:115]
	v_mfma_f32_16x16x32_bf16 v[116:119], v[160:163], v[192:195], v[116:119]
	v_mfma_f32_16x16x32_bf16 v[116:119], v[164:167], v[196:199], v[116:119]
	v_mfma_f32_16x16x32_bf16 v[120:123], v[168:171], v[192:195], v[120:123]
	v_mfma_f32_16x16x32_bf16 v[120:123], v[172:175], v[196:199], v[120:123]
	v_mfma_f32_16x16x32_bf16 v[124:127], v[160:163], v[200:203], v[124:127]
	v_mfma_f32_16x16x32_bf16 v[124:127], v[164:167], v[204:207], v[124:127]
	v_mfma_f32_16x16x32_bf16 v[128:131], v[168:171], v[200:203], v[128:131]
	v_mfma_f32_16x16x32_bf16 v[128:131], v[172:175], v[204:207], v[128:131]
	s_barrier
	s_add_i32 s8, s95, 2
	s_add_u32 s93, s93, 0x100
	s_addc_u32 s94, s94, 0
	s_add_u32 s66, s66, 0x100
	s_addc_u32 s67, s67, 0
	s_cmp_ge_i32 s95, s72
	s_mov_b32 s95, s8
	s_cbranch_scc0 .LBB0_1042
	v_readlane_b32 s94, v255, 39
	v_readlane_b32 s95, v255, 40
	s_branch .LBB0_1031

.LBB0_1156:
	ds_read_b128 v[136:139], v132
	ds_read_b128 v[140:143], v132 offset:1024
	ds_read_b128 v[144:147], v132 offset:2048
	ds_read_b128 v[148:151], v132 offset:3072
	ds_read_b128 v[152:155], v133
	ds_read_b128 v[156:159], v133 offset:1024
	ds_read_b128 v[160:163], v133 offset:2048
	ds_read_b128 v[164:167], v133 offset:3072
	s_cmp_eq_u32 s6, s82
	s_cselect_b32 s17, s27, s81
	s_cselect_b32 s16, s26, s80
	s_cselect_b32 s21, s51, s53
	s_cselect_b32 s20, s50, s52
	s_add_u32 s8, s52, 0xffffff80
	s_addc_u32 s9, s53, -1
	s_mov_b32 m0, s66
	s_mov_b64 s[18:19], s[8:9]
	ds_read_b128 v[168:171], v244 offset:8192
	ds_read_b128 v[172:175], v244 offset:9216
	ds_read_b128 v[176:179], v244 offset:10240
	ds_read_b128 v[180:183], v244 offset:11264
	ds_read_b128 v[184:187], v244 offset:12288
	ds_read_b128 v[188:191], v244 offset:13312
	ds_read_b128 v[192:195], v244 offset:14336
	ds_read_b128 v[196:199], v244 offset:15360
	s_add_u32 s8, s8, s28
	global_load_lds_dwordx4 v238, s[18:19]
	s_mov_b32 m0, s67
	s_addc_u32 s9, s9, s29
	global_load_lds_dwordx4 v2, s[18:19]
	s_mov_b32 m0, s68
	s_add_u32 s18, s16, 0x80
	global_load_lds_dwordx4 v238, s[8:9]
	s_mov_b32 m0, s69
	s_addc_u32 s19, s17, 0
	global_load_lds_dwordx4 v2, s[8:9]
	s_waitcnt vmcnt(8)
	s_waitcnt lgkmcnt(0)
	s_barrier
	s_waitcnt lgkmcnt(0)
	v_mfma_f32_16x16x32_bf16 v[4:7], v[136:139], v[168:171], v[4:7]
	v_mfma_f32_16x16x32_bf16 v[4:7], v[140:143], v[172:175], v[4:7]
	v_mfma_f32_16x16x32_bf16 v[8:11], v[144:147], v[168:171], v[8:11]
	v_mfma_f32_16x16x32_bf16 v[8:11], v[148:151], v[172:175], v[8:11]
	v_mfma_f32_16x16x32_bf16 v[12:15], v[136:139], v[176:179], v[12:15]
	v_mfma_f32_16x16x32_bf16 v[12:15], v[140:143], v[180:183], v[12:15]
	v_mfma_f32_16x16x32_bf16 v[16:19], v[144:147], v[176:179], v[16:19]
	v_mfma_f32_16x16x32_bf16 v[16:19], v[148:151], v[180:183], v[16:19]
	v_mfma_f32_16x16x32_bf16 v[20:23], v[136:139], v[184:187], v[20:23]
	v_mfma_f32_16x16x32_bf16 v[20:23], v[140:143], v[188:191], v[20:23]
	v_mfma_f32_16x16x32_bf16 v[24:27], v[144:147], v[184:187], v[24:27]
	v_mfma_f32_16x16x32_bf16 v[24:27], v[148:151], v[188:191], v[24:27]
	v_mfma_f32_16x16x32_bf16 v[28:31], v[136:139], v[192:195], v[28:31]
	v_mfma_f32_16x16x32_bf16 v[28:31], v[140:143], v[196:199], v[28:31]
	v_mfma_f32_16x16x32_bf16 v[32:35], v[144:147], v[192:195], v[32:35]
	v_mfma_f32_16x16x32_bf16 v[32:35], v[148:151], v[196:199], v[32:35]
	v_mfma_f32_16x16x32_bf16 v[36:39], v[152:155], v[168:171], v[36:39]
	v_mfma_f32_16x16x32_bf16 v[36:39], v[156:159], v[172:175], v[36:39]
	v_mfma_f32_16x16x32_bf16 v[40:43], v[160:163], v[168:171], v[40:43]
	v_mfma_f32_16x16x32_bf16 v[40:43], v[164:167], v[172:175], v[40:43]
	v_mfma_f32_16x16x32_bf16 v[44:47], v[152:155], v[176:179], v[44:47]
	v_mfma_f32_16x16x32_bf16 v[44:47], v[156:159], v[180:183], v[44:47]
	v_mfma_f32_16x16x32_bf16 v[48:51], v[160:163], v[176:179], v[48:51]
	v_mfma_f32_16x16x32_bf16 v[48:51], v[164:167], v[180:183], v[48:51]
	v_mfma_f32_16x16x32_bf16 v[52:55], v[152:155], v[184:187], v[52:55]
	v_mfma_f32_16x16x32_bf16 v[52:55], v[156:159], v[188:191], v[52:55]
	v_mfma_f32_16x16x32_bf16 v[56:59], v[160:163], v[184:187], v[56:59]
	v_mfma_f32_16x16x32_bf16 v[56:59], v[164:167], v[188:191], v[56:59]
	v_mfma_f32_16x16x32_bf16 v[60:63], v[152:155], v[192:195], v[60:63]
	v_mfma_f32_16x16x32_bf16 v[60:63], v[156:159], v[196:199], v[60:63]
	v_mfma_f32_16x16x32_bf16 v[64:67], v[160:163], v[192:195], v[64:67]
	v_mfma_f32_16x16x32_bf16 v[64:67], v[164:167], v[196:199], v[64:67]
	s_barrier
	s_mov_b32 m0, s72
	s_mov_b64 s[8:9], s[16:17]
	ds_read_b128 v[168:171], v244 offset:24576
	ds_read_b128 v[172:175], v244 offset:25600
	ds_read_b128 v[176:179], v244 offset:26624
	ds_read_b128 v[180:183], v244 offset:27648
	ds_read_b128 v[184:187], v244 offset:28672
	ds_read_b128 v[188:191], v244 offset:29696
	ds_read_b128 v[192:195], v244 offset:30720
	ds_read_b128 v[196:199], v244 offset:31744
	s_nop 0
	global_load_lds_dwordx4 v246, s[8:9]
	s_mov_b32 m0, s73
	s_nop 0
	global_load_lds_dwordx4 v245, s[8:9]
	s_add_u32 s8, s16, s28
	s_addc_u32 s9, s17, s29
	s_mov_b32 m0, s76
	s_nop 0
	global_load_lds_dwordx4 v246, s[8:9]
	s_mov_b32 m0, s77
	s_nop 0
	global_load_lds_dwordx4 v245, s[8:9]
	s_waitcnt vmcnt(6)
	s_waitcnt lgkmcnt(0)
	s_barrier
	s_waitcnt lgkmcnt(0)
	v_mfma_f32_16x16x32_bf16 v[68:71], v[136:139], v[168:171], v[68:71]
	v_mfma_f32_16x16x32_bf16 v[68:71], v[140:143], v[172:175], v[68:71]
	v_mfma_f32_16x16x32_bf16 v[72:75], v[144:147], v[168:171], v[72:75]
	v_mfma_f32_16x16x32_bf16 v[72:75], v[148:151], v[172:175], v[72:75]
	v_mfma_f32_16x16x32_bf16 v[76:79], v[136:139], v[176:179], v[76:79]
	v_mfma_f32_16x16x32_bf16 v[76:79], v[140:143], v[180:183], v[76:79]
	v_mfma_f32_16x16x32_bf16 v[80:83], v[144:147], v[176:179], v[80:83]
	v_mfma_f32_16x16x32_bf16 v[80:83], v[148:151], v[180:183], v[80:83]
	v_mfma_f32_16x16x32_bf16 v[84:87], v[136:139], v[184:187], v[84:87]
	v_mfma_f32_16x16x32_bf16 v[84:87], v[140:143], v[188:191], v[84:87]
	v_mfma_f32_16x16x32_bf16 v[88:91], v[144:147], v[184:187], v[88:91]
	v_mfma_f32_16x16x32_bf16 v[88:91], v[148:151], v[188:191], v[88:91]
	v_mfma_f32_16x16x32_bf16 v[92:95], v[136:139], v[192:195], v[92:95]
	v_mfma_f32_16x16x32_bf16 v[92:95], v[140:143], v[196:199], v[92:95]
	v_mfma_f32_16x16x32_bf16 v[96:99], v[144:147], v[192:195], v[96:99]
	v_mfma_f32_16x16x32_bf16 v[96:99], v[148:151], v[196:199], v[96:99]
	v_mfma_f32_16x16x32_bf16 v[100:103], v[152:155], v[168:171], v[100:103]
	v_mfma_f32_16x16x32_bf16 v[100:103], v[156:159], v[172:175], v[100:103]
	v_mfma_f32_16x16x32_bf16 v[104:107], v[160:163], v[168:171], v[104:107]
	v_mfma_f32_16x16x32_bf16 v[104:107], v[164:167], v[172:175], v[104:107]
	v_mfma_f32_16x16x32_bf16 v[108:111], v[152:155], v[176:179], v[108:111]
	v_mfma_f32_16x16x32_bf16 v[108:111], v[156:159], v[180:183], v[108:111]
	v_mfma_f32_16x16x32_bf16 v[112:115], v[160:163], v[176:179], v[112:115]
	v_mfma_f32_16x16x32_bf16 v[112:115], v[164:167], v[180:183], v[112:115]
	v_mfma_f32_16x16x32_bf16 v[116:119], v[152:155], v[184:187], v[116:119]
	v_mfma_f32_16x16x32_bf16 v[116:119], v[156:159], v[188:191], v[116:119]
	v_mfma_f32_16x16x32_bf16 v[120:123], v[160:163], v[184:187], v[120:123]
	v_mfma_f32_16x16x32_bf16 v[120:123], v[164:167], v[188:191], v[120:123]
	v_mfma_f32_16x16x32_bf16 v[124:127], v[152:155], v[192:195], v[124:127]
	v_mfma_f32_16x16x32_bf16 v[124:127], v[156:159], v[196:199], v[124:127]
	v_mfma_f32_16x16x32_bf16 v[128:131], v[160:163], v[192:195], v[128:131]
	v_mfma_f32_16x16x32_bf16 v[128:131], v[164:167], v[196:199], v[128:131]
	s_barrier
	ds_read_b128 v[136:139], v134
	ds_read_b128 v[140:143], v134 offset:1024
	ds_read_b128 v[144:147], v134 offset:2048
	ds_read_b128 v[148:151], v134 offset:3072
	ds_read_b128 v[152:155], v135
	ds_read_b128 v[156:159], v135 offset:1024
	ds_read_b128 v[160:163], v135 offset:2048
	ds_read_b128 v[164:167], v135 offset:3072
	s_mov_b32 m0, s58
	s_mov_b64 s[8:9], s[20:21]
	ds_read_b128 v[168:171], v244 offset:40960
	ds_read_b128 v[172:175], v244 offset:41984
	ds_read_b128 v[176:179], v244 offset:43008
	ds_read_b128 v[180:183], v244 offset:44032
	ds_read_b128 v[184:187], v244 offset:45056
	ds_read_b128 v[188:191], v244 offset:46080
	ds_read_b128 v[192:195], v244 offset:47104
	ds_read_b128 v[196:199], v244 offset:48128
	s_nop 0
	global_load_lds_dwordx4 v238, s[8:9]
	s_mov_b32 m0, s59
	s_nop 0
	global_load_lds_dwordx4 v2, s[8:9]
	s_add_u32 s8, s20, s28
	s_addc_u32 s9, s21, s29
	s_mov_b32 m0, s60
	s_nop 0
	global_load_lds_dwordx4 v238, s[8:9]
	s_mov_b32 m0, s61
	s_nop 0
	global_load_lds_dwordx4 v2, s[8:9]
	s_waitcnt vmcnt(8)
	s_waitcnt lgkmcnt(0)
	s_barrier
	s_waitcnt lgkmcnt(0)
	v_mfma_f32_16x16x32_bf16 v[4:7], v[136:139], v[168:171], v[4:7]
	v_mfma_f32_16x16x32_bf16 v[4:7], v[140:143], v[172:175], v[4:7]
	v_mfma_f32_16x16x32_bf16 v[8:11], v[144:147], v[168:171], v[8:11]
	v_mfma_f32_16x16x32_bf16 v[8:11], v[148:151], v[172:175], v[8:11]
	v_mfma_f32_16x16x32_bf16 v[12:15], v[136:139], v[176:179], v[12:15]
	v_mfma_f32_16x16x32_bf16 v[12:15], v[140:143], v[180:183], v[12:15]
	v_mfma_f32_16x16x32_bf16 v[16:19], v[144:147], v[176:179], v[16:19]
	v_mfma_f32_16x16x32_bf16 v[16:19], v[148:151], v[180:183], v[16:19]
	v_mfma_f32_16x16x32_bf16 v[20:23], v[136:139], v[184:187], v[20:23]
	v_mfma_f32_16x16x32_bf16 v[20:23], v[140:143], v[188:191], v[20:23]
	v_mfma_f32_16x16x32_bf16 v[24:27], v[144:147], v[184:187], v[24:27]
	v_mfma_f32_16x16x32_bf16 v[24:27], v[148:151], v[188:191], v[24:27]
	v_mfma_f32_16x16x32_bf16 v[28:31], v[136:139], v[192:195], v[28:31]
	v_mfma_f32_16x16x32_bf16 v[28:31], v[140:143], v[196:199], v[28:31]
	v_mfma_f32_16x16x32_bf16 v[32:35], v[144:147], v[192:195], v[32:35]
	v_mfma_f32_16x16x32_bf16 v[32:35], v[148:151], v[196:199], v[32:35]
	v_mfma_f32_16x16x32_bf16 v[36:39], v[152:155], v[168:171], v[36:39]
	v_mfma_f32_16x16x32_bf16 v[36:39], v[156:159], v[172:175], v[36:39]
	v_mfma_f32_16x16x32_bf16 v[40:43], v[160:163], v[168:171], v[40:43]
	v_mfma_f32_16x16x32_bf16 v[40:43], v[164:167], v[172:175], v[40:43]
	v_mfma_f32_16x16x32_bf16 v[44:47], v[152:155], v[176:179], v[44:47]
	v_mfma_f32_16x16x32_bf16 v[44:47], v[156:159], v[180:183], v[44:47]
	v_mfma_f32_16x16x32_bf16 v[48:51], v[160:163], v[176:179], v[48:51]
	v_mfma_f32_16x16x32_bf16 v[48:51], v[164:167], v[180:183], v[48:51]
	v_mfma_f32_16x16x32_bf16 v[52:55], v[152:155], v[184:187], v[52:55]
	v_mfma_f32_16x16x32_bf16 v[52:55], v[156:159], v[188:191], v[52:55]
	v_mfma_f32_16x16x32_bf16 v[56:59], v[160:163], v[184:187], v[56:59]
	v_mfma_f32_16x16x32_bf16 v[56:59], v[164:167], v[188:191], v[56:59]
	v_mfma_f32_16x16x32_bf16 v[60:63], v[152:155], v[192:195], v[60:63]
	v_mfma_f32_16x16x32_bf16 v[60:63], v[156:159], v[196:199], v[60:63]
	v_mfma_f32_16x16x32_bf16 v[64:67], v[160:163], v[192:195], v[64:67]
	v_mfma_f32_16x16x32_bf16 v[64:67], v[164:167], v[196:199], v[64:67]
	s_barrier
	s_mov_b32 m0, s42
	s_mov_b64 s[8:9], s[18:19]
	ds_read_b128 v[168:171], v244 offset:57344
	ds_read_b128 v[172:175], v244 offset:58368
	ds_read_b128 v[176:179], v244 offset:59392
	ds_read_b128 v[180:183], v244 offset:60416
	ds_read_b128 v[184:187], v244 offset:61440
	ds_read_b128 v[188:191], v244 offset:62464
	ds_read_b128 v[192:195], v244 offset:63488
	ds_read_b128 v[196:199], v244 offset:64512
	s_nop 0
	global_load_lds_dwordx4 v246, s[8:9]
	s_mov_b32 m0, s43
	s_nop 0
	global_load_lds_dwordx4 v245, s[8:9]
	s_add_u32 s8, s18, s28
	s_addc_u32 s9, s19, s29
	s_mov_b32 m0, s78
	s_nop 0
	global_load_lds_dwordx4 v246, s[8:9]
	s_mov_b32 m0, s79
	s_nop 0
	global_load_lds_dwordx4 v245, s[8:9]
	s_waitcnt vmcnt(6)
	s_waitcnt lgkmcnt(0)
	s_barrier
	s_waitcnt lgkmcnt(0)
	v_mfma_f32_16x16x32_bf16 v[68:71], v[136:139], v[168:171], v[68:71]
	v_mfma_f32_16x16x32_bf16 v[68:71], v[140:143], v[172:175], v[68:71]
	v_mfma_f32_16x16x32_bf16 v[72:75], v[144:147], v[168:171], v[72:75]
	v_mfma_f32_16x16x32_bf16 v[72:75], v[148:151], v[172:175], v[72:75]
	v_mfma_f32_16x16x32_bf16 v[76:79], v[136:139], v[176:179], v[76:79]
	v_mfma_f32_16x16x32_bf16 v[76:79], v[140:143], v[180:183], v[76:79]
	v_mfma_f32_16x16x32_bf16 v[80:83], v[144:147], v[176:179], v[80:83]
	v_mfma_f32_16x16x32_bf16 v[80:83], v[148:151], v[180:183], v[80:83]
	v_mfma_f32_16x16x32_bf16 v[84:87], v[136:139], v[184:187], v[84:87]
	v_mfma_f32_16x16x32_bf16 v[84:87], v[140:143], v[188:191], v[84:87]
	v_mfma_f32_16x16x32_bf16 v[88:91], v[144:147], v[184:187], v[88:91]
	v_mfma_f32_16x16x32_bf16 v[88:91], v[148:151], v[188:191], v[88:91]
	v_mfma_f32_16x16x32_bf16 v[92:95], v[136:139], v[192:195], v[92:95]
	v_mfma_f32_16x16x32_bf16 v[92:95], v[140:143], v[196:199], v[92:95]
	v_mfma_f32_16x16x32_bf16 v[96:99], v[144:147], v[192:195], v[96:99]
	v_mfma_f32_16x16x32_bf16 v[96:99], v[148:151], v[196:199], v[96:99]
	v_mfma_f32_16x16x32_bf16 v[100:103], v[152:155], v[168:171], v[100:103]
	v_mfma_f32_16x16x32_bf16 v[100:103], v[156:159], v[172:175], v[100:103]
	v_mfma_f32_16x16x32_bf16 v[104:107], v[160:163], v[168:171], v[104:107]
	v_mfma_f32_16x16x32_bf16 v[104:107], v[164:167], v[172:175], v[104:107]
	v_mfma_f32_16x16x32_bf16 v[108:111], v[152:155], v[176:179], v[108:111]
	v_mfma_f32_16x16x32_bf16 v[108:111], v[156:159], v[180:183], v[108:111]
	v_mfma_f32_16x16x32_bf16 v[112:115], v[160:163], v[176:179], v[112:115]
	v_mfma_f32_16x16x32_bf16 v[112:115], v[164:167], v[180:183], v[112:115]
	v_mfma_f32_16x16x32_bf16 v[116:119], v[152:155], v[184:187], v[116:119]
	v_mfma_f32_16x16x32_bf16 v[116:119], v[156:159], v[188:191], v[116:119]
	v_mfma_f32_16x16x32_bf16 v[120:123], v[160:163], v[184:187], v[120:123]
	v_mfma_f32_16x16x32_bf16 v[120:123], v[164:167], v[188:191], v[120:123]
	v_mfma_f32_16x16x32_bf16 v[124:127], v[152:155], v[192:195], v[124:127]
	v_mfma_f32_16x16x32_bf16 v[124:127], v[156:159], v[196:199], v[124:127]
	v_mfma_f32_16x16x32_bf16 v[128:131], v[160:163], v[192:195], v[128:131]
	v_mfma_f32_16x16x32_bf16 v[128:131], v[164:167], v[196:199], v[128:131]
	s_barrier
	s_add_i32 s8, s82, 2
	s_add_u32 s80, s80, 0x100
	s_addc_u32 s81, s81, 0
	s_add_u32 s52, s52, 0x100
	s_addc_u32 s53, s53, 0
	s_cmp_ge_i32 s82, s6
	s_mov_b32 s82, s8
	s_cbranch_scc0 .LBB0_1156

.LBB0_1176:
	ds_read_b128 v[136:139], v132
	ds_read_b128 v[140:143], v132 offset:1024
	ds_read_b128 v[144:147], v132 offset:2048
	ds_read_b128 v[148:151], v132 offset:3072
	ds_read_b128 v[152:155], v133
	ds_read_b128 v[156:159], v133 offset:1024
	ds_read_b128 v[160:163], v133 offset:2048
	ds_read_b128 v[164:167], v133 offset:3072
	s_cmp_eq_u32 s6, s80
	s_cselect_b32 s17, s21, s79
	s_cselect_b32 s16, s20, s78
	s_cselect_b32 s27, s41, s51
	s_cselect_b32 s26, s40, s50
	s_add_u32 s8, s50, 0xffffff80
	s_addc_u32 s9, s51, -1
	s_mov_b32 m0, s64
	s_mov_b64 s[18:19], s[8:9]
	ds_read_b128 v[168:171], v244
	ds_read_b128 v[172:175], v244 offset:1024
	ds_read_b128 v[176:179], v244 offset:2048
	ds_read_b128 v[180:183], v244 offset:3072
	ds_read_b128 v[184:187], v244 offset:4096
	ds_read_b128 v[188:191], v244 offset:5120
	ds_read_b128 v[192:195], v244 offset:6144
	ds_read_b128 v[196:199], v244 offset:7168
	s_add_u32 s8, s8, s28
	global_load_lds_dwordx4 v238, s[18:19]
	s_mov_b32 m0, s65
	s_addc_u32 s9, s9, s29
	global_load_lds_dwordx4 v2, s[18:19]
	s_mov_b32 m0, s66
	s_add_u32 s18, s16, 0x80
	global_load_lds_dwordx4 v238, s[8:9]
	s_mov_b32 m0, s67
	s_addc_u32 s19, s17, 0
	global_load_lds_dwordx4 v2, s[8:9]
	s_waitcnt vmcnt(8)
	s_waitcnt lgkmcnt(0)
	s_barrier
	s_waitcnt lgkmcnt(0)
	v_mfma_f32_16x16x32_bf16 v[4:7], v[136:139], v[168:171], v[4:7]
	v_mfma_f32_16x16x32_bf16 v[4:7], v[140:143], v[172:175], v[4:7]
	v_mfma_f32_16x16x32_bf16 v[8:11], v[144:147], v[168:171], v[8:11]
	v_mfma_f32_16x16x32_bf16 v[8:11], v[148:151], v[172:175], v[8:11]
	v_mfma_f32_16x16x32_bf16 v[12:15], v[136:139], v[176:179], v[12:15]
	v_mfma_f32_16x16x32_bf16 v[12:15], v[140:143], v[180:183], v[12:15]
	v_mfma_f32_16x16x32_bf16 v[16:19], v[144:147], v[176:179], v[16:19]
	v_mfma_f32_16x16x32_bf16 v[16:19], v[148:151], v[180:183], v[16:19]
	v_mfma_f32_16x16x32_bf16 v[20:23], v[136:139], v[184:187], v[20:23]
	v_mfma_f32_16x16x32_bf16 v[20:23], v[140:143], v[188:191], v[20:23]
	v_mfma_f32_16x16x32_bf16 v[24:27], v[144:147], v[184:187], v[24:27]
	v_mfma_f32_16x16x32_bf16 v[24:27], v[148:151], v[188:191], v[24:27]
	v_mfma_f32_16x16x32_bf16 v[28:31], v[136:139], v[192:195], v[28:31]
	v_mfma_f32_16x16x32_bf16 v[28:31], v[140:143], v[196:199], v[28:31]
	v_mfma_f32_16x16x32_bf16 v[32:35], v[144:147], v[192:195], v[32:35]
	v_mfma_f32_16x16x32_bf16 v[32:35], v[148:151], v[196:199], v[32:35]
	v_mfma_f32_16x16x32_bf16 v[36:39], v[152:155], v[168:171], v[36:39]
	v_mfma_f32_16x16x32_bf16 v[36:39], v[156:159], v[172:175], v[36:39]
	v_mfma_f32_16x16x32_bf16 v[40:43], v[160:163], v[168:171], v[40:43]
	v_mfma_f32_16x16x32_bf16 v[40:43], v[164:167], v[172:175], v[40:43]
	v_mfma_f32_16x16x32_bf16 v[44:47], v[152:155], v[176:179], v[44:47]
	v_mfma_f32_16x16x32_bf16 v[44:47], v[156:159], v[180:183], v[44:47]
	v_mfma_f32_16x16x32_bf16 v[48:51], v[160:163], v[176:179], v[48:51]
	v_mfma_f32_16x16x32_bf16 v[48:51], v[164:167], v[180:183], v[48:51]
	v_mfma_f32_16x16x32_bf16 v[52:55], v[152:155], v[184:187], v[52:55]
	v_mfma_f32_16x16x32_bf16 v[52:55], v[156:159], v[188:191], v[52:55]
	v_mfma_f32_16x16x32_bf16 v[56:59], v[160:163], v[184:187], v[56:59]
	v_mfma_f32_16x16x32_bf16 v[56:59], v[164:167], v[188:191], v[56:59]
	v_mfma_f32_16x16x32_bf16 v[60:63], v[152:155], v[192:195], v[60:63]
	v_mfma_f32_16x16x32_bf16 v[60:63], v[156:159], v[196:199], v[60:63]
	v_mfma_f32_16x16x32_bf16 v[64:67], v[160:163], v[192:195], v[64:67]
	v_mfma_f32_16x16x32_bf16 v[64:67], v[164:167], v[196:199], v[64:67]
	s_barrier
	s_mov_b32 m0, s68
	s_mov_b64 s[8:9], s[16:17]
	ds_read_b128 v[168:171], v244 offset:16384
	ds_read_b128 v[172:175], v244 offset:17408
	ds_read_b128 v[176:179], v244 offset:18432
	ds_read_b128 v[180:183], v244 offset:19456
	ds_read_b128 v[184:187], v244 offset:20480
	ds_read_b128 v[188:191], v244 offset:21504
	ds_read_b128 v[192:195], v244 offset:22528
	ds_read_b128 v[196:199], v244 offset:23552
	s_nop 0
	global_load_lds_dwordx4 v246, s[8:9]
	s_mov_b32 m0, s69
	s_nop 0
	global_load_lds_dwordx4 v245, s[8:9]
	s_add_u32 s8, s16, s28
	s_addc_u32 s9, s17, s29
	s_mov_b32 m0, s72
	s_nop 0
	global_load_lds_dwordx4 v246, s[8:9]
	s_mov_b32 m0, s73
	s_nop 0
	global_load_lds_dwordx4 v245, s[8:9]
	s_waitcnt vmcnt(6)
	s_waitcnt lgkmcnt(0)
	s_barrier
	s_waitcnt lgkmcnt(0)
	v_mfma_f32_16x16x32_bf16 v[68:71], v[136:139], v[168:171], v[68:71]
	v_mfma_f32_16x16x32_bf16 v[68:71], v[140:143], v[172:175], v[68:71]
	v_mfma_f32_16x16x32_bf16 v[72:75], v[144:147], v[168:171], v[72:75]
	v_mfma_f32_16x16x32_bf16 v[72:75], v[148:151], v[172:175], v[72:75]
	v_mfma_f32_16x16x32_bf16 v[76:79], v[136:139], v[176:179], v[76:79]
	v_mfma_f32_16x16x32_bf16 v[76:79], v[140:143], v[180:183], v[76:79]
	v_mfma_f32_16x16x32_bf16 v[80:83], v[144:147], v[176:179], v[80:83]
	v_mfma_f32_16x16x32_bf16 v[80:83], v[148:151], v[180:183], v[80:83]
	v_mfma_f32_16x16x32_bf16 v[84:87], v[136:139], v[184:187], v[84:87]
	v_mfma_f32_16x16x32_bf16 v[84:87], v[140:143], v[188:191], v[84:87]
	v_mfma_f32_16x16x32_bf16 v[88:91], v[144:147], v[184:187], v[88:91]
	v_mfma_f32_16x16x32_bf16 v[88:91], v[148:151], v[188:191], v[88:91]
	v_mfma_f32_16x16x32_bf16 v[92:95], v[136:139], v[192:195], v[92:95]
	v_mfma_f32_16x16x32_bf16 v[92:95], v[140:143], v[196:199], v[92:95]
	v_mfma_f32_16x16x32_bf16 v[96:99], v[144:147], v[192:195], v[96:99]
	v_mfma_f32_16x16x32_bf16 v[96:99], v[148:151], v[196:199], v[96:99]
	v_mfma_f32_16x16x32_bf16 v[100:103], v[152:155], v[168:171], v[100:103]
	v_mfma_f32_16x16x32_bf16 v[100:103], v[156:159], v[172:175], v[100:103]
	v_mfma_f32_16x16x32_bf16 v[104:107], v[160:163], v[168:171], v[104:107]
	v_mfma_f32_16x16x32_bf16 v[104:107], v[164:167], v[172:175], v[104:107]
	v_mfma_f32_16x16x32_bf16 v[108:111], v[152:155], v[176:179], v[108:111]
	v_mfma_f32_16x16x32_bf16 v[108:111], v[156:159], v[180:183], v[108:111]
	v_mfma_f32_16x16x32_bf16 v[112:115], v[160:163], v[176:179], v[112:115]
	v_mfma_f32_16x16x32_bf16 v[112:115], v[164:167], v[180:183], v[112:115]
	v_mfma_f32_16x16x32_bf16 v[116:119], v[152:155], v[184:187], v[116:119]
	v_mfma_f32_16x16x32_bf16 v[116:119], v[156:159], v[188:191], v[116:119]
	v_mfma_f32_16x16x32_bf16 v[120:123], v[160:163], v[184:187], v[120:123]
	v_mfma_f32_16x16x32_bf16 v[120:123], v[164:167], v[188:191], v[120:123]
	v_mfma_f32_16x16x32_bf16 v[124:127], v[152:155], v[192:195], v[124:127]
	v_mfma_f32_16x16x32_bf16 v[124:127], v[156:159], v[196:199], v[124:127]
	v_mfma_f32_16x16x32_bf16 v[128:131], v[160:163], v[192:195], v[128:131]
	v_mfma_f32_16x16x32_bf16 v[128:131], v[164:167], v[196:199], v[128:131]
	s_barrier
	ds_read_b128 v[136:139], v134
	ds_read_b128 v[140:143], v134 offset:1024
	ds_read_b128 v[144:147], v134 offset:2048
	ds_read_b128 v[148:151], v134 offset:3072
	ds_read_b128 v[152:155], v135
	ds_read_b128 v[156:159], v135 offset:1024
	ds_read_b128 v[160:163], v135 offset:2048
	ds_read_b128 v[164:167], v135 offset:3072
	s_mov_b32 m0, s53
	s_mov_b64 s[8:9], s[26:27]
	ds_read_b128 v[168:171], v244 offset:32768
	ds_read_b128 v[172:175], v244 offset:33792
	ds_read_b128 v[176:179], v244 offset:34816
	ds_read_b128 v[180:183], v244 offset:35840
	ds_read_b128 v[184:187], v244 offset:36864
	ds_read_b128 v[188:191], v244 offset:37888
	ds_read_b128 v[192:195], v244 offset:38912
	ds_read_b128 v[196:199], v244 offset:39936
	s_nop 0
	global_load_lds_dwordx4 v238, s[8:9]
	s_mov_b32 m0, s57
	s_nop 0
	global_load_lds_dwordx4 v2, s[8:9]
	s_add_u32 s8, s26, s28
	s_addc_u32 s9, s27, s29
	s_mov_b32 m0, s58
	s_nop 0
	global_load_lds_dwordx4 v238, s[8:9]
	s_mov_b32 m0, s59
	s_nop 0
	global_load_lds_dwordx4 v2, s[8:9]
	s_waitcnt vmcnt(8)
	s_waitcnt lgkmcnt(0)
	s_barrier
	s_waitcnt lgkmcnt(0)
	v_mfma_f32_16x16x32_bf16 v[4:7], v[136:139], v[168:171], v[4:7]
	v_mfma_f32_16x16x32_bf16 v[4:7], v[140:143], v[172:175], v[4:7]
	v_mfma_f32_16x16x32_bf16 v[8:11], v[144:147], v[168:171], v[8:11]
	v_mfma_f32_16x16x32_bf16 v[8:11], v[148:151], v[172:175], v[8:11]
	v_mfma_f32_16x16x32_bf16 v[12:15], v[136:139], v[176:179], v[12:15]
	v_mfma_f32_16x16x32_bf16 v[12:15], v[140:143], v[180:183], v[12:15]
	v_mfma_f32_16x16x32_bf16 v[16:19], v[144:147], v[176:179], v[16:19]
	v_mfma_f32_16x16x32_bf16 v[16:19], v[148:151], v[180:183], v[16:19]
	v_mfma_f32_16x16x32_bf16 v[20:23], v[136:139], v[184:187], v[20:23]
	v_mfma_f32_16x16x32_bf16 v[20:23], v[140:143], v[188:191], v[20:23]
	v_mfma_f32_16x16x32_bf16 v[24:27], v[144:147], v[184:187], v[24:27]
	v_mfma_f32_16x16x32_bf16 v[24:27], v[148:151], v[188:191], v[24:27]
	v_mfma_f32_16x16x32_bf16 v[28:31], v[136:139], v[192:195], v[28:31]
	v_mfma_f32_16x16x32_bf16 v[28:31], v[140:143], v[196:199], v[28:31]
	v_mfma_f32_16x16x32_bf16 v[32:35], v[144:147], v[192:195], v[32:35]
	v_mfma_f32_16x16x32_bf16 v[32:35], v[148:151], v[196:199], v[32:35]
	v_mfma_f32_16x16x32_bf16 v[36:39], v[152:155], v[168:171], v[36:39]
	v_mfma_f32_16x16x32_bf16 v[36:39], v[156:159], v[172:175], v[36:39]
	v_mfma_f32_16x16x32_bf16 v[40:43], v[160:163], v[168:171], v[40:43]
	v_mfma_f32_16x16x32_bf16 v[40:43], v[164:167], v[172:175], v[40:43]
	v_mfma_f32_16x16x32_bf16 v[44:47], v[152:155], v[176:179], v[44:47]
	v_mfma_f32_16x16x32_bf16 v[44:47], v[156:159], v[180:183], v[44:47]
	v_mfma_f32_16x16x32_bf16 v[48:51], v[160:163], v[176:179], v[48:51]
	v_mfma_f32_16x16x32_bf16 v[48:51], v[164:167], v[180:183], v[48:51]
	v_mfma_f32_16x16x32_bf16 v[52:55], v[152:155], v[184:187], v[52:55]
	v_mfma_f32_16x16x32_bf16 v[52:55], v[156:159], v[188:191], v[52:55]
	v_mfma_f32_16x16x32_bf16 v[56:59], v[160:163], v[184:187], v[56:59]
	v_mfma_f32_16x16x32_bf16 v[56:59], v[164:167], v[188:191], v[56:59]
	v_mfma_f32_16x16x32_bf16 v[60:63], v[152:155], v[192:195], v[60:63]
	v_mfma_f32_16x16x32_bf16 v[60:63], v[156:159], v[196:199], v[60:63]
	v_mfma_f32_16x16x32_bf16 v[64:67], v[160:163], v[192:195], v[64:67]
	v_mfma_f32_16x16x32_bf16 v[64:67], v[164:167], v[196:199], v[64:67]
	s_barrier
	s_mov_b32 m0, s42
	s_mov_b64 s[8:9], s[18:19]
	ds_read_b128 v[168:171], v244 offset:49152
	ds_read_b128 v[172:175], v244 offset:50176
	ds_read_b128 v[176:179], v244 offset:51200
	ds_read_b128 v[180:183], v244 offset:52224
	ds_read_b128 v[184:187], v244 offset:53248
	ds_read_b128 v[188:191], v244 offset:54272
	ds_read_b128 v[192:195], v244 offset:55296
	ds_read_b128 v[196:199], v244 offset:56320
	s_nop 0
	global_load_lds_dwordx4 v246, s[8:9]
	s_mov_b32 m0, s43
	s_nop 0
	global_load_lds_dwordx4 v245, s[8:9]
	s_add_u32 s8, s18, s28
	s_addc_u32 s9, s19, s29
	s_mov_b32 m0, s76
	s_nop 0
	global_load_lds_dwordx4 v246, s[8:9]
	s_mov_b32 m0, s77
	s_nop 0
	global_load_lds_dwordx4 v245, s[8:9]
	s_waitcnt vmcnt(6)
	s_waitcnt lgkmcnt(0)
	s_barrier
	s_waitcnt lgkmcnt(0)
	v_mfma_f32_16x16x32_bf16 v[68:71], v[136:139], v[168:171], v[68:71]
	v_mfma_f32_16x16x32_bf16 v[68:71], v[140:143], v[172:175], v[68:71]
	v_mfma_f32_16x16x32_bf16 v[72:75], v[144:147], v[168:171], v[72:75]
	v_mfma_f32_16x16x32_bf16 v[72:75], v[148:151], v[172:175], v[72:75]
	v_mfma_f32_16x16x32_bf16 v[76:79], v[136:139], v[176:179], v[76:79]
	v_mfma_f32_16x16x32_bf16 v[76:79], v[140:143], v[180:183], v[76:79]
	v_mfma_f32_16x16x32_bf16 v[80:83], v[144:147], v[176:179], v[80:83]
	v_mfma_f32_16x16x32_bf16 v[80:83], v[148:151], v[180:183], v[80:83]
	v_mfma_f32_16x16x32_bf16 v[84:87], v[136:139], v[184:187], v[84:87]
	v_mfma_f32_16x16x32_bf16 v[84:87], v[140:143], v[188:191], v[84:87]
	v_mfma_f32_16x16x32_bf16 v[88:91], v[144:147], v[184:187], v[88:91]
	v_mfma_f32_16x16x32_bf16 v[88:91], v[148:151], v[188:191], v[88:91]
	v_mfma_f32_16x16x32_bf16 v[92:95], v[136:139], v[192:195], v[92:95]
	v_mfma_f32_16x16x32_bf16 v[92:95], v[140:143], v[196:199], v[92:95]
	v_mfma_f32_16x16x32_bf16 v[96:99], v[144:147], v[192:195], v[96:99]
	v_mfma_f32_16x16x32_bf16 v[96:99], v[148:151], v[196:199], v[96:99]
	v_mfma_f32_16x16x32_bf16 v[100:103], v[152:155], v[168:171], v[100:103]
	v_mfma_f32_16x16x32_bf16 v[100:103], v[156:159], v[172:175], v[100:103]
	v_mfma_f32_16x16x32_bf16 v[104:107], v[160:163], v[168:171], v[104:107]
	v_mfma_f32_16x16x32_bf16 v[104:107], v[164:167], v[172:175], v[104:107]
	v_mfma_f32_16x16x32_bf16 v[108:111], v[152:155], v[176:179], v[108:111]
	v_mfma_f32_16x16x32_bf16 v[108:111], v[156:159], v[180:183], v[108:111]
	v_mfma_f32_16x16x32_bf16 v[112:115], v[160:163], v[176:179], v[112:115]
	v_mfma_f32_16x16x32_bf16 v[112:115], v[164:167], v[180:183], v[112:115]
	v_mfma_f32_16x16x32_bf16 v[116:119], v[152:155], v[184:187], v[116:119]
	v_mfma_f32_16x16x32_bf16 v[116:119], v[156:159], v[188:191], v[116:119]
	v_mfma_f32_16x16x32_bf16 v[120:123], v[160:163], v[184:187], v[120:123]
	v_mfma_f32_16x16x32_bf16 v[120:123], v[164:167], v[188:191], v[120:123]
	v_mfma_f32_16x16x32_bf16 v[124:127], v[152:155], v[192:195], v[124:127]
	v_mfma_f32_16x16x32_bf16 v[124:127], v[156:159], v[196:199], v[124:127]
	v_mfma_f32_16x16x32_bf16 v[128:131], v[160:163], v[192:195], v[128:131]
	v_mfma_f32_16x16x32_bf16 v[128:131], v[164:167], v[196:199], v[128:131]
	s_barrier
	s_add_i32 s8, s80, 2
	s_add_u32 s78, s78, 0x100
	s_addc_u32 s79, s79, 0
	s_add_u32 s50, s50, 0x100
	s_addc_u32 s51, s51, 0
	s_cmp_ge_i32 s80, s6
	s_mov_b32 s80, s8
	s_cbranch_scc0 .LBB0_1176
